# exact trims: drop (0 + d0) add in fix-up items and the identity v_max after attention permlane max hops
# baseline (speedup 1.0000x reference)
; __device__ __forceinline__ void attn_unit(int u, int l, const bf16_t* proj, const float* a_lambda, const float* a_norm_w, bf16_t* ha, LAS unsigned char* lds) {
;     ...
;             float mx = -1e30f;
; #pragma unroll
;             for (int it = 0; it < 4; ++it) mx = fmaxf(mx, fmaxf(fmaxf(s[it][0], s[it][1]), fmaxf(s[it][2], s[it][3])));
;             mx = fmaxf(mx, __shfl_xor(mx, 16)); mx = fmaxf(mx, __shfl_xor(mx, 32));
;             const float mnew = (mx > mrow[n] + 8.0f) ? mx : mrow[n];
;             float ps = 0.f;
; #pragma unroll
;             for (int it = 0; it < 4; ++it)
; #pragma unroll
;                 for (int r = 0; r < 4; ++r) { s[it][r] = __builtin_amdgcn_exp2f(s[it][r] - mnew); ps += s[it][r]; }
;             ps += __shfl_xor(ps, 16); ps += __shfl_xor(ps, 32);
;             if (__builtin_amdgcn_ballot_w64(mnew != mrow[n]) != 0ull) {
;                 const float alpha = __builtin_amdgcn_exp2f(mrow[n] - mnew);
;                 lrow[n] = lrow[n] * alpha;
; #pragma unroll
;                 for (int e = 0; e < 8; ++e) O[n][e] = O[n][e] * alpha;
;             }
.LBB0_289:
	v_max_f32_e32 v2, v115, v115
	v_max_f32_e32 v3, v114, v114
	v_max_f32_e32 v2, v3, v2
	v_max_f32_e32 v3, v111, v111
	v_max_f32_e32 v141, v110, v110
	v_max_f32_e32 v3, v141, v3
	v_max3_f32 v2, v112, v113, v2
	v_max3_f32 v3, v108, v109, v3
	v_max3_f32 v2, v2, s93, v3
	v_max_f32_e32 v3, v107, v107
	v_max_f32_e32 v141, v106, v106
	v_max_f32_e32 v3, v141, v3
	v_max_f32_e32 v141, v103, v103
	v_max_f32_e32 v142, v102, v102
	v_max_f32_e32 v141, v142, v141
	v_max3_f32 v3, v104, v105, v3
	v_max3_f32 v141, v100, v101, v141
	v_max3_f32 v2, v2, v3, v141
	v_mov_b32_e32 v3, v2
	s_nop 1
	v_permlane16_swap_b32 v3, v2
	s_waitcnt lgkmcnt(0)
	v_max_f32_e32 v2, v2, v3
	v_mov_b32_e32 v3, v2
	s_nop 1
	v_permlane32_swap_b32 v3, v2
	s_waitcnt lgkmcnt(0)
	v_max_f32_e32 v2, v2, v3
	v_add_f32_e32 v3, 0x41000000, v174
	v_cmp_gt_f32_e32 vcc, v2, v3
	s_nop 1
	v_cndmask_b32_e32 v2, v174, v2, vcc
	v_sub_f32_e32 v3, v112, v2
	v_exp_f32_e32 v151, v3
	v_sub_f32_e32 v3, v113, v2
	v_exp_f32_e32 v152, v3
	v_sub_f32_e32 v3, v114, v2
	v_exp_f32_e32 v153, v3
	v_sub_f32_e32 v3, v115, v2
	v_exp_f32_e32 v154, v3
	v_sub_f32_e32 v108, v108, v2
	v_add_f32_e32 v3, 0, v151
	v_exp_f32_e32 v155, v108
	v_sub_f32_e32 v108, v109, v2
	v_add_f32_e32 v3, v152, v3
	v_exp_f32_e32 v156, v108
	v_sub_f32_e32 v108, v110, v2
	v_add_f32_e32 v3, v153, v3
	v_exp_f32_e32 v157, v108
	v_sub_f32_e32 v108, v111, v2
	v_add_f32_e32 v3, v154, v3
	v_exp_f32_e32 v158, v108
	v_sub_f32_e32 v104, v104, v2
	v_add_f32_e32 v3, v155, v3
	v_exp_f32_e32 v142, v104
	v_sub_f32_e32 v104, v105, v2
	v_add_f32_e32 v3, v156, v3
	v_exp_f32_e32 v143, v104
	v_sub_f32_e32 v104, v106, v2
	v_add_f32_e32 v3, v157, v3
	v_exp_f32_e32 v144, v104
	v_sub_f32_e32 v104, v107, v2
	v_add_f32_e32 v3, v158, v3
	v_exp_f32_e32 v145, v104
	v_sub_f32_e32 v100, v100, v2
	v_add_f32_e32 v3, v142, v3
	v_exp_f32_e32 v146, v100
	v_sub_f32_e32 v100, v101, v2
	v_add_f32_e32 v3, v143, v3
	v_exp_f32_e32 v147, v100
	v_sub_f32_e32 v100, v102, v2
	v_add_f32_e32 v3, v144, v3
	v_exp_f32_e32 v148, v100
	v_sub_f32_e32 v100, v103, v2
	v_add_f32_e32 v3, v145, v3
	v_exp_f32_e32 v149, v100
	v_add_f32_e32 v3, v146, v3
	v_add_f32_e32 v3, v147, v3
	v_add_f32_e32 v3, v148, v3
	v_add_f32_e32 v3, v149, v3
	v_mov_b32_e32 v100, v3
	s_nop 1
	v_permlane16_swap_b32 v100, v3
	v_cmp_neq_f32_e32 vcc, v2, v174
	s_waitcnt lgkmcnt(0)
	v_add_f32_e32 v3, v3, v100
	v_mov_b32_e32 v141, v3
	s_nop 1
	v_permlane32_swap_b32 v141, v3
	s_cbranch_vccz .LBB0_291
	v_sub_f32_e32 v100, v174, v2
	v_exp_f32_e32 v100, v100
	s_nop 0
	v_mul_f32_e32 v129, v129, v100
	v_pk_mul_f32 v[66:67], v[66:67], v[100:101] op_sel_hi:[1,0]
	v_pk_mul_f32 v[64:65], v[64:65], v[100:101] op_sel_hi:[1,0]
	v_pk_mul_f32 v[62:63], v[62:63], v[100:101] op_sel_hi:[1,0]
	v_pk_mul_f32 v[60:61], v[60:61], v[100:101] op_sel_hi:[1,0]
	v_pk_mul_f32 v[50:51], v[50:51], v[100:101] op_sel_hi:[1,0]
	v_pk_mul_f32 v[48:49], v[48:49], v[100:101] op_sel_hi:[1,0]
	v_pk_mul_f32 v[42:43], v[42:43], v[100:101] op_sel_hi:[1,0]
	v_pk_mul_f32 v[40:41], v[40:41], v[100:101] op_sel_hi:[1,0]
	v_pk_mul_f32 v[34:35], v[34:35], v[100:101] op_sel_hi:[1,0]
	v_pk_mul_f32 v[32:33], v[32:33], v[100:101] op_sel_hi:[1,0]
	v_pk_mul_f32 v[26:27], v[26:27], v[100:101] op_sel_hi:[1,0]
	v_pk_mul_f32 v[24:25], v[24:25], v[100:101] op_sel_hi:[1,0]
	v_pk_mul_f32 v[14:15], v[14:15], v[100:101] op_sel_hi:[1,0]
	v_pk_mul_f32 v[12:13], v[12:13], v[100:101] op_sel_hi:[1,0]
	v_pk_mul_f32 v[10:11], v[10:11], v[100:101] op_sel_hi:[1,0]
	v_pk_mul_f32 v[8:9], v[8:9], v[100:101] op_sel_hi:[1,0]

; __device__ __forceinline__ void attn_unit(int u, int l, const bf16_t* proj, const float* a_lambda, const float* a_norm_w, bf16_t* ha, LAS unsigned char* lds) {
;     ...
;             float mx = -1e30f;
; #pragma unroll
;             for (int it = 0; it < 4; ++it) mx = fmaxf(mx, fmaxf(fmaxf(s[it][0], s[it][1]), fmaxf(s[it][2], s[it][3])));
;             mx = fmaxf(mx, __shfl_xor(mx, 16)); mx = fmaxf(mx, __shfl_xor(mx, 32));
;             const float mnew = (mx > mrow[n] + 8.0f) ? mx : mrow[n];
;             float ps = 0.f;
; #pragma unroll
;             for (int it = 0; it < 4; ++it)
; #pragma unroll
;                 for (int r = 0; r < 4; ++r) { s[it][r] = __builtin_amdgcn_exp2f(s[it][r] - mnew); ps += s[it][r]; }
;             ps += __shfl_xor(ps, 16); ps += __shfl_xor(ps, 32);
;             if (__builtin_amdgcn_ballot_w64(mnew != mrow[n]) != 0ull) {
;                 const float alpha = __builtin_amdgcn_exp2f(mrow[n] - mnew);
;                 lrow[n] = lrow[n] * alpha;
; #pragma unroll
;                 for (int e = 0; e < 8; ++e) O[n][e] = O[n][e] * alpha;
;             }
.LBB0_293:
	v_max_f32_e32 v1, v103, v103
	v_max_f32_e32 v159, v102, v102
	v_max_f32_e32 v1, v159, v1
	v_max_f32_e32 v159, v107, v107
	v_max_f32_e32 v160, v106, v106
	v_max_f32_e32 v159, v160, v159
	v_max3_f32 v1, v100, v101, v1
	v_max3_f32 v159, v104, v105, v159
	v_max3_f32 v1, v1, s93, v159
	v_max_f32_e32 v159, v111, v111
	v_max_f32_e32 v160, v110, v110
	v_max_f32_e32 v159, v160, v159
	v_max_f32_e32 v160, v115, v115
	v_max_f32_e32 v161, v114, v114
	v_max_f32_e32 v160, v161, v160
	v_max3_f32 v159, v108, v109, v159
	v_max3_f32 v160, v112, v113, v160
	v_max3_f32 v1, v1, v159, v160
	v_mov_b32_e32 v159, v1
	s_nop 1
	v_permlane16_swap_b32 v159, v1
	s_waitcnt lgkmcnt(0)
	v_max_f32_e32 v1, v1, v159
	v_mov_b32_e32 v159, v1
	s_nop 1
	v_permlane32_swap_b32 v159, v1
	s_waitcnt lgkmcnt(0)
	v_max_f32_e32 v1, v1, v159
	v_add_f32_e32 v159, 0x41000000, v150
	v_cmp_gt_f32_e32 vcc, v1, v159
	s_nop 1
	v_cndmask_b32_e32 v1, v150, v1, vcc
	v_sub_f32_e32 v100, v100, v1
	v_exp_f32_e32 v159, v100
	v_sub_f32_e32 v100, v101, v1
	v_exp_f32_e32 v160, v100
	v_sub_f32_e32 v100, v102, v1
	v_exp_f32_e32 v161, v100
	v_sub_f32_e32 v100, v103, v1
	v_exp_f32_e32 v162, v100
	v_sub_f32_e32 v101, v104, v1
	v_add_f32_e32 v100, 0, v159
	v_exp_f32_e32 v163, v101
	v_sub_f32_e32 v101, v105, v1
	v_add_f32_e32 v100, v160, v100
	v_exp_f32_e32 v164, v101
	v_sub_f32_e32 v101, v106, v1
	v_add_f32_e32 v100, v161, v100
	v_exp_f32_e32 v165, v101
	v_sub_f32_e32 v101, v107, v1
	v_add_f32_e32 v100, v162, v100
	v_exp_f32_e32 v166, v101
	v_sub_f32_e32 v101, v108, v1
	v_add_f32_e32 v100, v163, v100
	v_exp_f32_e32 v102, v101
	v_sub_f32_e32 v101, v109, v1
	v_add_f32_e32 v100, v164, v100
	v_exp_f32_e32 v103, v101
	v_sub_f32_e32 v101, v110, v1
	v_add_f32_e32 v100, v165, v100
	v_exp_f32_e32 v104, v101
	v_sub_f32_e32 v101, v111, v1
	v_add_f32_e32 v100, v166, v100
	v_exp_f32_e32 v105, v101
	v_sub_f32_e32 v101, v112, v1
	v_add_f32_e32 v100, v102, v100
	v_exp_f32_e32 v106, v101
	v_sub_f32_e32 v101, v113, v1
	v_add_f32_e32 v100, v103, v100
	v_exp_f32_e32 v107, v101
	v_sub_f32_e32 v101, v114, v1
	v_add_f32_e32 v100, v104, v100
	v_exp_f32_e32 v108, v101
	v_sub_f32_e32 v101, v115, v1
	v_add_f32_e32 v100, v105, v100
	v_exp_f32_e32 v109, v101
	v_add_f32_e32 v100, v106, v100
	v_add_f32_e32 v100, v107, v100
	v_add_f32_e32 v100, v108, v100
	v_add_f32_e32 v100, v109, v100
	v_mov_b32_e32 v101, v100
	s_nop 1
	v_permlane16_swap_b32 v101, v100
	v_cmp_neq_f32_e32 vcc, v1, v150
	s_waitcnt lgkmcnt(0)
	v_add_f32_e32 v100, v100, v101
	v_mov_b32_e32 v101, v100
	s_nop 1
	v_permlane32_swap_b32 v101, v100
	s_cbranch_vccz .LBB0_295
	v_sub_f32_e32 v110, v150, v1
	v_exp_f32_e32 v110, v110
	s_nop 0
	v_mul_f32_e32 v117, v117, v110
	v_pk_mul_f32 v[54:55], v[54:55], v[110:111] op_sel_hi:[1,0]
	v_pk_mul_f32 v[52:53], v[52:53], v[110:111] op_sel_hi:[1,0]
	v_pk_mul_f32 v[58:59], v[58:59], v[110:111] op_sel_hi:[1,0]
	v_pk_mul_f32 v[56:57], v[56:57], v[110:111] op_sel_hi:[1,0]
	v_pk_mul_f32 v[46:47], v[46:47], v[110:111] op_sel_hi:[1,0]
	v_pk_mul_f32 v[44:45], v[44:45], v[110:111] op_sel_hi:[1,0]
	v_pk_mul_f32 v[38:39], v[38:39], v[110:111] op_sel_hi:[1,0]
	v_pk_mul_f32 v[36:37], v[36:37], v[110:111] op_sel_hi:[1,0]
	v_pk_mul_f32 v[30:31], v[30:31], v[110:111] op_sel_hi:[1,0]
	v_pk_mul_f32 v[28:29], v[28:29], v[110:111] op_sel_hi:[1,0]
	v_pk_mul_f32 v[22:23], v[22:23], v[110:111] op_sel_hi:[1,0]
	v_pk_mul_f32 v[20:21], v[20:21], v[110:111] op_sel_hi:[1,0]
	v_pk_mul_f32 v[18:19], v[18:19], v[110:111] op_sel_hi:[1,0]
	v_pk_mul_f32 v[16:17], v[16:17], v[110:111] op_sel_hi:[1,0]
	v_pk_mul_f32 v[6:7], v[6:7], v[110:111] op_sel_hi:[1,0]
	v_pk_mul_f32 v[4:5], v[4:5], v[110:111] op_sel_hi:[1,0]

; __device__ __forceinline__ int launder_i(int x) { asm volatile("" : "+v"(x)); return x; }
; #define m_norm_w KIN(8)
; __global__ void __launch_bounds__(NTHREADS, 2) fwd_megakernel(Params P) {
;     ...
;         { const int tid = launder_i(threadIdx.x), lane = tid & 63, wid = tid >> 6;
;         const bf16_t* q_mp = B_MPART; const float* q_dp = B_DPART; const bf16_t* q_hp = B_HPART; const float* q_mnw = m_norm_w; const float* q_gnw = g_norm_w; const bf16_t* q_proj = B_PROJ; bf16_t* q_hcat = B_HCAT;
;         const int step = G * NWAVES;
;         for (int it0 = bid * NWAVES + wid; it0 < T * 4; it0 += 2 * step) {
;             f32x4 v[2]; float den[2]; u32x2 mo[2]; bool ok[2];
; #pragma unroll
;             for (int q = 0; q < 2; ++q) {
;                 const int it = it0 + q * step; ok[q] = it < T * 4; const int itc = ok[q] ? it : it0;
;                 const int row = itc >> 2, h = itc & 3; const size_t o = (size_t)row * 1024 + h * 256 + 4 * lane;
;                 v[q] = (f32x4){0.f, 0.f, 0.f, 0.f}; den[q] = 0.f;
; #pragma unroll
;                 for (int dq = 0; dq < 4; ++dq) { const u32x2 p = *(const u32x2*)(q_mp + (size_t)dq * T * 1024 + o);
;                     v[q][0] += bflo(p.x); v[q][1] += bfhi(p.x); v[q][2] += bflo(p.y); v[q][3] += bfhi(p.y); den[q] += q_dp[(size_t)dq * T * 4 + (size_t)row * 4 + h]; }
;                 mo[q] = *(const u32x2*)(q_proj + (size_t)row * NP + C_MO + h * 256 + 4 * lane);
.LBB0_541:
	s_or_b64 exec, exec, s[28:29]
	v_mov_b32_e32 v9, v252
	s_waitcnt lgkmcnt(0)
	s_barrier
	v_readlane_b32 s4, v253, 2
	v_ashrrev_i32_e32 v8, 6, v9
	s_mov_b64 s[48:49], s[0:1]
	v_add_u32_e32 v1, s4, v8
	s_mov_b32 s4, 0x8000
	s_mov_b64 s[44:45], s[0:1]
	s_mov_b64 s[42:43], s[0:1]
	s_mov_b64 s[34:35], s[0:1]
	s_mov_b64 s[40:41], s[0:1]
	s_mov_b64 s[46:47], s[0:1]
	s_mov_b64 s[38:39], s[0:1]
	v_cmp_gt_i32_e32 vcc, s4, v1
	s_and_saveexec_b64 s[28:29], vcc
	s_cbranch_execz .LBB0_550
	v_and_b32_e32 v2, 64, v217
	v_add_u32_e32 v2, 64, v2
	v_xor_b32_e32 v3, 1, v217
	v_cmp_lt_i32_e32 vcc, v3, v2
	s_load_dwordx2 s[4:5], s[48:49], 0xc0
	s_load_dwordx2 s[6:7], s[44:45], 0xc0
	s_nop 0
	s_load_dwordx2 s[42:43], s[42:43], 0xc0
	s_nop 0
	s_load_dwordx2 s[8:9], s[46:47], 0xc0
	v_cndmask_b32_e32 v3, v217, v3, vcc
	v_lshlrev_b32_e32 v7, 2, v3
	v_xor_b32_e32 v3, 2, v217
	v_cmp_lt_i32_e32 vcc, v3, v2
	s_waitcnt lgkmcnt(0)
	s_add_u32 s48, s4, 0x31000000
	s_addc_u32 s49, s5, 0
	v_cndmask_b32_e32 v3, v217, v3, vcc
	v_lshlrev_b32_e32 v35, 2, v3
	v_xor_b32_e32 v3, 4, v217
	v_cmp_lt_i32_e32 vcc, v3, v2
	s_add_u32 s50, s6, 0x3b0c0000
	s_addc_u32 s51, s7, 0
	v_cndmask_b32_e32 v3, v217, v3, vcc
	v_lshlrev_b32_e32 v36, 2, v3
	v_xor_b32_e32 v3, 8, v217
	v_cmp_lt_i32_e32 vcc, v3, v2
	s_load_dwordx2 s[4:5], s[34:35], 0x40
	s_load_dwordx2 s[44:45], s[40:41], 0x60
	v_cndmask_b32_e32 v3, v217, v3, vcc
	v_lshlrev_b32_e32 v37, 2, v3
	v_xor_b32_e32 v3, 16, v217
	v_cmp_lt_i32_e32 vcc, v3, v2
	s_add_u32 s34, s8, 0x19000000
	s_load_dwordx2 s[46:47], s[38:39], 0xc0
	v_cndmask_b32_e32 v3, v217, v3, vcc
	s_addc_u32 s35, s9, 0
	v_lshlrev_b32_e32 v38, 2, v3
	v_xor_b32_e32 v3, 32, v217
	s_lshl_b32 s36, s82, 10
	v_cmp_lt_i32_e32 vcc, v3, v2
	s_lshl_b64 s[6:7], s[36:37], 2
	v_and_b32_e32 v4, 63, v9
	v_cndmask_b32_e32 v2, v217, v3, vcc
	s_waitcnt lgkmcnt(0)
	s_add_u32 s4, s4, s6
	v_lshlrev_b32_e32 v40, 2, v2
	s_addc_u32 s5, s5, s7
	v_lshlrev_b32_e32 v2, 4, v4
	v_mov_b32_e32 v3, v0
	v_lshlrev_b32_e32 v10, 3, v4
	v_mov_b32_e32 v11, v0
	v_bfe_u32 v9, v9, 6, 2
	v_lshlrev_b32_e32 v6, 2, v4
	v_lshl_add_u64 v[2:3], s[4:5], 0, v[2:3]
	v_lshl_add_u64 v[4:5], s[46:47], 0, v[10:11]
	s_mov_b64 s[4:5], 0x2a000000
	v_lshlrev_b32_e32 v12, 9, v9
	v_mov_b32_e32 v13, v0
	v_lshl_add_u64 v[4:5], v[4:5], 0, s[4:5]
	v_lshl_add_u64 v[12:13], s[48:49], 0, v[12:13]
	v_readlane_b32 s4, v254, 52
	v_lshlrev_b32_e32 v14, 8, v9
	v_lshl_add_u64 v[10:11], v[12:13], 0, v[10:11]
	v_lshlrev_b32_e32 v12, 2, v9
	v_mov_b32_e32 v13, v0
	v_lshl_add_u32 v39, v8, 8, s4
	v_lshl_add_u64 v[12:13], s[50:51], 0, v[12:13]
	s_mov_b64 s[52:53], 0
	v_lshlrev_b32_e32 v14, 1, v14
	v_mov_b32_e32 v41, v39
	v_mov_b32_e32 v42, v1
	s_cmpk_lg_i32 s78, 0x100
	s_cbranch_scc1 .LBB0_544
	v_readfirstlane_b32 s4, v1
	v_lshlrev_b32_e32 v8, 1, v6
	v_mov_b32_e32 v19, 0
	s_and_b32 s5, s4, 3
	s_lshr_b32 s4, s4, 2
	s_lshl_b32 s6, s4, 11
	s_lshl_b32 s7, s5, 9
	s_add_u32 s6, s6, s7
	v_add_u32_e32 v15, s6, v8
	v_mov_b32_e32 v33, v15
	s_lshl_b32 s6, s4, 4
	s_lshl_b32 s8, s5, 2
	s_add_u32 s6, s6, s8
	v_mov_b32_e32 v16, s6
	s_mul_i32 s8, s4, s25
	s_add_u32 s8, s8, s7
	s_add_u32 s8, s8, 0x1800
	v_add_u32_e32 v17, s8, v8
	s_lshl_b32 s9, s5, 10
	v_mov_b32_e32 v18, s9
	v_lshl_add_u64 v[18:19], v[2:3], 0, v[18:19]
	global_load_dwordx4 v[20:23], v[18:19], off
	s_add_u32 s4, s48, 0x1000000
	s_addc_u32 s5, s49, 0
	s_add_u32 s6, s48, 0x2000000
	s_addc_u32 s7, s49, 0
	s_add_u32 s8, s48, 0x3000000
	s_addc_u32 s9, s49, 0
	s_add_u32 s38, s46, 0x2a000000
	s_addc_u32 s39, s47, 0
	global_load_dwordx2 v[54:55], v15, s[48:49]
	global_load_dwordx2 v[56:57], v15, s[4:5]
	global_load_dwordx2 v[58:59], v15, s[6:7]
	global_load_dwordx2 v[60:61], v15, s[8:9]
	v_add_u32_e32 v24, 0x20000, v16
	v_add_u32_e32 v25, 0x40000, v16
	v_add_u32_e32 v26, 0x60000, v16
	global_load_dword v62, v16, s[50:51]
	global_load_dword v63, v24, s[50:51]
	global_load_dword v64, v25, s[50:51]
	global_load_dword v65, v26, s[50:51]
	global_load_dwordx2 v[66:67], v17, s[34:35]
	v_add_u32_e32 v15, 0x100000, v15
	v_add_u32_e32 v16, 0x2000, v16
	v_add_u32_e32 v17, 0x1100000, v17
	global_load_dwordx2 v[68:69], v15, s[48:49]
	global_load_dwordx2 v[70:71], v15, s[4:5]
	global_load_dwordx2 v[72:73], v15, s[6:7]
	global_load_dwordx2 v[74:75], v15, s[8:9]
	v_add_u32_e32 v24, 0x20000, v16
	v_add_u32_e32 v25, 0x40000, v16
	v_add_u32_e32 v26, 0x60000, v16
	global_load_dword v76, v16, s[50:51]
	global_load_dword v77, v24, s[50:51]
	global_load_dword v78, v25, s[50:51]
	global_load_dword v79, v26, s[50:51]
	global_load_dwordx2 v[80:81], v17, s[34:35]
	v_add_u32_e32 v15, 0x100000, v15
	v_add_u32_e32 v16, 0x2000, v16
	v_add_u32_e32 v17, 0x1100000, v17
	global_load_dwordx2 v[82:83], v15, s[48:49]
	global_load_dwordx2 v[84:85], v15, s[4:5]
	global_load_dwordx2 v[86:87], v15, s[6:7]
	global_load_dwordx2 v[88:89], v15, s[8:9]
	v_add_u32_e32 v24, 0x20000, v16
	v_add_u32_e32 v25, 0x40000, v16
	v_add_u32_e32 v26, 0x60000, v16
	global_load_dword v90, v16, s[50:51]
	global_load_dword v91, v24, s[50:51]
	global_load_dword v92, v25, s[50:51]
	global_load_dword v93, v26, s[50:51]
	global_load_dwordx2 v[94:95], v17, s[34:35]
	v_add_u32_e32 v15, 0x100000, v15
	v_add_u32_e32 v16, 0x2000, v16
	v_add_u32_e32 v17, 0x1100000, v17
	global_load_dwordx2 v[96:97], v15, s[48:49]
	global_load_dwordx2 v[98:99], v15, s[4:5]
	global_load_dwordx2 v[100:101], v15, s[6:7]
	global_load_dwordx2 v[102:103], v15, s[8:9]
	v_add_u32_e32 v24, 0x20000, v16
	v_add_u32_e32 v25, 0x40000, v16
	v_add_u32_e32 v26, 0x60000, v16
	global_load_dword v104, v16, s[50:51]
	global_load_dword v105, v24, s[50:51]
	global_load_dword v106, v25, s[50:51]
	global_load_dword v107, v26, s[50:51]
; __global__ void __launch_bounds__(NTHREADS, 2) fwd_megakernel(Params P) {
;     ...
;             for (int q = 0; q < 2; ++q) {
;                 const int it = it0 + q * step; ok[q] = it < T * 4; const int itc = ok[q] ? it : it0;
;                 const int row = itc >> 2, h = itc & 3; const size_t o = (size_t)row * 1024 + h * 256 + 4 * lane;
;                 v[q] = (f32x4){0.f, 0.f, 0.f, 0.f}; den[q] = 0.f;
; #pragma unroll
;                 for (int dq = 0; dq < 4; ++dq) { const u32x2 p = *(const u32x2*)(q_mp + (size_t)dq * T * 1024 + o);
;                     v[q][0] += bflo(p.x); v[q][1] += bfhi(p.x); v[q][2] += bflo(p.y); v[q][3] += bfhi(p.y); den[q] += q_dp[(size_t)dq * T * 4 + (size_t)row * 4 + h]; }
;                 mo[q] = *(const u32x2*)(q_proj + (size_t)row * NP + C_MO + h * 256 + 4 * lane);
;             }
; #pragma unroll
;             for (int q = 0; q < 2; ++q) {
;                 const int it = it0 + q * step; const int itc = ok[q] ? it : it0; const int row = itc >> 2, h = itc & 3;
;                 const f32x4 x = v[q] * (1.0f / fmaxf(fabsf(den[q]), 1.0f));
;                 const float ss = wave_sum((x[0] * x[0] + x[1] * x[1]) + (x[2] * x[2] + x[3] * x[3]));
;                 const float rsn = 1.0f / sqrtf(ss * (1.0f / 256.0f) + NORM_EPS);
	global_load_dwordx2 v[108:109], v17, s[34:35]
	v_add_u32_e32 v15, 0x100000, v15
	v_add_u32_e32 v16, 0x2000, v16
	v_add_u32_e32 v17, 0x1100000, v17
	global_load_dwordx2 v[110:111], v15, s[48:49]
	global_load_dwordx2 v[112:113], v15, s[4:5]
	global_load_dwordx2 v[114:115], v15, s[6:7]
	global_load_dwordx2 v[116:117], v15, s[8:9]
	v_add_u32_e32 v24, 0x20000, v16
	v_add_u32_e32 v25, 0x40000, v16
	v_add_u32_e32 v26, 0x60000, v16
	global_load_dword v118, v16, s[50:51]
	global_load_dword v119, v24, s[50:51]
	global_load_dword v120, v25, s[50:51]
	global_load_dword v121, v26, s[50:51]
	global_load_dwordx2 v[122:123], v17, s[34:35]
	v_add_u32_e32 v15, 0x100000, v15
	v_add_u32_e32 v16, 0x2000, v16
	v_add_u32_e32 v17, 0x1100000, v17
	global_load_dwordx2 v[124:125], v15, s[48:49]
	global_load_dwordx2 v[126:127], v15, s[4:5]
	global_load_dwordx2 v[128:129], v15, s[6:7]
	global_load_dwordx2 v[130:131], v15, s[8:9]
	v_add_u32_e32 v24, 0x20000, v16
	v_add_u32_e32 v25, 0x40000, v16
	v_add_u32_e32 v26, 0x60000, v16
	global_load_dword v132, v16, s[50:51]
	global_load_dword v133, v24, s[50:51]
	global_load_dword v134, v25, s[50:51]
	global_load_dword v135, v26, s[50:51]
	global_load_dwordx2 v[136:137], v17, s[34:35]
	v_add_u32_e32 v15, 0x100000, v15
	v_add_u32_e32 v16, 0x2000, v16
	v_add_u32_e32 v17, 0x1100000, v17
	global_load_dwordx2 v[138:139], v15, s[48:49]
	global_load_dwordx2 v[140:141], v15, s[4:5]
	global_load_dwordx2 v[142:143], v15, s[6:7]
	global_load_dwordx2 v[144:145], v15, s[8:9]
	v_add_u32_e32 v24, 0x20000, v16
	v_add_u32_e32 v25, 0x40000, v16
	v_add_u32_e32 v26, 0x60000, v16
	global_load_dword v146, v16, s[50:51]
	global_load_dword v147, v24, s[50:51]
	global_load_dword v148, v25, s[50:51]
	global_load_dword v149, v26, s[50:51]
	global_load_dwordx2 v[150:151], v17, s[34:35]
	v_add_u32_e32 v15, 0x100000, v15
	v_add_u32_e32 v16, 0x2000, v16
	v_add_u32_e32 v17, 0x1100000, v17
	global_load_dwordx2 v[152:153], v15, s[48:49]
	global_load_dwordx2 v[154:155], v15, s[4:5]
	global_load_dwordx2 v[156:157], v15, s[6:7]
	global_load_dwordx2 v[158:159], v15, s[8:9]
	v_add_u32_e32 v24, 0x20000, v16
	v_add_u32_e32 v25, 0x40000, v16
	v_add_u32_e32 v26, 0x60000, v16
	global_load_dword v160, v16, s[50:51]
	global_load_dword v161, v24, s[50:51]
	global_load_dword v162, v25, s[50:51]
	global_load_dword v163, v26, s[50:51]
	global_load_dwordx2 v[164:165], v17, s[34:35]
	v_add_u32_e32 v15, 0x100000, v15
	v_add_u32_e32 v16, 0x2000, v16
	v_add_u32_e32 v17, 0x1100000, v17
	s_waitcnt vmcnt(36)
	v_lshlrev_b32_e32 v166, 16, v54
	v_and_b32_e32 v167, 0xffff0000, v54
	v_lshlrev_b32_e32 v168, 16, v55
	v_and_b32_e32 v169, 0xffff0000, v55
	v_lshlrev_b32_e32 v190, 16, v56
	v_and_b32_e32 v191, 0xffff0000, v56
	v_lshlrev_b32_e32 v192, 16, v57
	v_and_b32_e32 v193, 0xffff0000, v57
	v_pk_add_f32 v[166:167], v[166:167], v[190:191]
	v_pk_add_f32 v[168:169], v[168:169], v[192:193]
	v_lshlrev_b32_e32 v190, 16, v58
	v_and_b32_e32 v191, 0xffff0000, v58
	v_lshlrev_b32_e32 v192, 16, v59
	v_and_b32_e32 v193, 0xffff0000, v59
	v_pk_add_f32 v[166:167], v[166:167], v[190:191]
	v_pk_add_f32 v[168:169], v[168:169], v[192:193]
	v_lshlrev_b32_e32 v190, 16, v60
	v_and_b32_e32 v191, 0xffff0000, v60
	v_lshlrev_b32_e32 v192, 16, v61
	v_and_b32_e32 v193, 0xffff0000, v61
	v_pk_add_f32 v[166:167], v[166:167], v[190:191]
	v_pk_add_f32 v[168:169], v[168:169], v[192:193]
	v_add_f32_e32 v194, v62, v63
	v_add_f32_e32 v194, v194, v64
	v_add_f32_e32 v194, v194, v65
	v_max_f32_e64 v194, |v194|, 1.0
	v_div_scale_f32 v196, s[52:53], v194, v194, 1.0
	v_rcp_f32_e32 v197, v196
	s_nop 0
	v_fma_f32 v198, -v196, v197, 1.0
	v_fmac_f32_e32 v197, v198, v197
	v_div_scale_f32 v198, vcc, 1.0, v194, 1.0
	v_mul_f32_e32 v199, v198, v197
	v_fma_f32 v195, -v196, v199, v198
	v_fmac_f32_e32 v199, v195, v197
	v_fma_f32 v196, -v196, v199, v198
	v_div_fmas_f32 v196, v196, v197, v199
	v_div_fixup_f32 v195, v196, v194, 1.0
	v_mul_f32_e32 v166, v166, v195
	v_mul_f32_e32 v167, v167, v195
	v_mul_f32_e32 v168, v168, v195
	v_mul_f32_e32 v169, v169, v195
	v_mul_f32_e32 v190, v166, v166
	v_mul_f32_e32 v191, v167, v167
	v_mul_f32_e32 v192, v168, v168
	v_mul_f32_e32 v193, v169, v169
	v_add_f32_e32 v190, v191, v190
	v_add_f32_e32 v192, v192, v193
	v_add_f32_e32 v170, v190, v192
	v_lshlrev_b32_e32 v172, 16, v68
	v_and_b32_e32 v173, 0xffff0000, v68
	v_lshlrev_b32_e32 v174, 16, v69
	v_and_b32_e32 v175, 0xffff0000, v69
	v_lshlrev_b32_e32 v190, 16, v70
	v_and_b32_e32 v191, 0xffff0000, v70
	v_lshlrev_b32_e32 v192, 16, v71
	v_and_b32_e32 v193, 0xffff0000, v71
	v_pk_add_f32 v[172:173], v[172:173], v[190:191]
	v_pk_add_f32 v[174:175], v[174:175], v[192:193]
	v_lshlrev_b32_e32 v190, 16, v72
	v_and_b32_e32 v191, 0xffff0000, v72
	v_lshlrev_b32_e32 v192, 16, v73
	v_and_b32_e32 v193, 0xffff0000, v73
	v_pk_add_f32 v[172:173], v[172:173], v[190:191]
	v_pk_add_f32 v[174:175], v[174:175], v[192:193]
	v_lshlrev_b32_e32 v190, 16, v74
	v_and_b32_e32 v191, 0xffff0000, v74
	v_lshlrev_b32_e32 v192, 16, v75
	v_and_b32_e32 v193, 0xffff0000, v75
	v_pk_add_f32 v[172:173], v[172:173], v[190:191]
	v_pk_add_f32 v[174:175], v[174:175], v[192:193]
	v_add_f32_e32 v194, v76, v77
	v_add_f32_e32 v194, v194, v78
	v_add_f32_e32 v194, v194, v79
	v_max_f32_e64 v194, |v194|, 1.0
	v_div_scale_f32 v196, s[52:53], v194, v194, 1.0
	v_rcp_f32_e32 v197, v196
	s_nop 0
	v_fma_f32 v198, -v196, v197, 1.0
	v_fmac_f32_e32 v197, v198, v197
	v_div_scale_f32 v198, vcc, 1.0, v194, 1.0
	v_mul_f32_e32 v199, v198, v197
	v_fma_f32 v195, -v196, v199, v198
	v_fmac_f32_e32 v199, v195, v197
	v_fma_f32 v196, -v196, v199, v198
	v_div_fmas_f32 v196, v196, v197, v199
	v_div_fixup_f32 v195, v196, v194, 1.0
; __global__ void __launch_bounds__(NTHREADS, 2) fwd_megakernel(Params P) {
;     ...
;                 for (int dq = 0; dq < 4; ++dq) { const u32x2 p = *(const u32x2*)(q_mp + (size_t)dq * T * 1024 + o);
;                     v[q][0] += bflo(p.x); v[q][1] += bfhi(p.x); v[q][2] += bflo(p.y); v[q][3] += bfhi(p.y); den[q] += q_dp[(size_t)dq * T * 4 + (size_t)row * 4 + h]; }
;                 mo[q] = *(const u32x2*)(q_proj + (size_t)row * NP + C_MO + h * 256 + 4 * lane);
;             }
; #pragma unroll
;             for (int q = 0; q < 2; ++q) {
;                 const int it = it0 + q * step; const int itc = ok[q] ? it : it0; const int row = itc >> 2, h = itc & 3;
;                 const f32x4 x = v[q] * (1.0f / fmaxf(fabsf(den[q]), 1.0f));
;                 const float ss = wave_sum((x[0] * x[0] + x[1] * x[1]) + (x[2] * x[2] + x[3] * x[3]));
;                 const float rsn = 1.0f / sqrtf(ss * (1.0f / 256.0f) + NORM_EPS);
	v_mul_f32_e32 v172, v172, v195
	v_mul_f32_e32 v173, v173, v195
	v_mul_f32_e32 v174, v174, v195
	v_mul_f32_e32 v175, v175, v195
	v_mul_f32_e32 v191, v175, v175
	v_mul_f32_e32 v190, v173, v173
	v_fmac_f32_e32 v190, v172, v172
	v_fmac_f32_e32 v191, v174, v174
	v_add_f32_e32 v176, v190, v191
	v_lshlrev_b32_e32 v178, 16, v82
	v_and_b32_e32 v179, 0xffff0000, v82
	v_lshlrev_b32_e32 v180, 16, v83
	v_and_b32_e32 v181, 0xffff0000, v83
	v_lshlrev_b32_e32 v190, 16, v84
	v_and_b32_e32 v191, 0xffff0000, v84
	v_lshlrev_b32_e32 v192, 16, v85
	v_and_b32_e32 v193, 0xffff0000, v85
	v_pk_add_f32 v[178:179], v[178:179], v[190:191]
	v_pk_add_f32 v[180:181], v[180:181], v[192:193]
	v_lshlrev_b32_e32 v190, 16, v86
	v_and_b32_e32 v191, 0xffff0000, v86
	v_lshlrev_b32_e32 v192, 16, v87
	v_and_b32_e32 v193, 0xffff0000, v87
	v_pk_add_f32 v[178:179], v[178:179], v[190:191]
	v_pk_add_f32 v[180:181], v[180:181], v[192:193]
	v_lshlrev_b32_e32 v190, 16, v88
	v_and_b32_e32 v191, 0xffff0000, v88
	v_lshlrev_b32_e32 v192, 16, v89
	v_and_b32_e32 v193, 0xffff0000, v89
	v_pk_add_f32 v[178:179], v[178:179], v[190:191]
	v_pk_add_f32 v[180:181], v[180:181], v[192:193]
	v_add_f32_e32 v194, v90, v91
	v_add_f32_e32 v194, v194, v92
	v_add_f32_e32 v194, v194, v93
	v_max_f32_e64 v194, |v194|, 1.0
	v_div_scale_f32 v196, s[52:53], v194, v194, 1.0
	v_rcp_f32_e32 v197, v196
	s_nop 0
	v_fma_f32 v198, -v196, v197, 1.0
	v_fmac_f32_e32 v197, v198, v197
	v_div_scale_f32 v198, vcc, 1.0, v194, 1.0
	v_mul_f32_e32 v199, v198, v197
	v_fma_f32 v195, -v196, v199, v198
	v_fmac_f32_e32 v199, v195, v197
	v_fma_f32 v196, -v196, v199, v198
	v_div_fmas_f32 v196, v196, v197, v199
	v_div_fixup_f32 v195, v196, v194, 1.0
	v_mul_f32_e32 v178, v178, v195
	v_mul_f32_e32 v179, v179, v195
	v_mul_f32_e32 v180, v180, v195
	v_mul_f32_e32 v181, v181, v195
	v_mul_f32_e32 v190, v178, v178
	v_mul_f32_e32 v191, v179, v179
	v_mul_f32_e32 v192, v180, v180
	v_mul_f32_e32 v193, v181, v181
	v_add_f32_e32 v190, v191, v190
	v_add_f32_e32 v192, v192, v193
	v_add_f32_e32 v182, v190, v192
	v_lshlrev_b32_e32 v184, 16, v96
	v_and_b32_e32 v185, 0xffff0000, v96
	v_lshlrev_b32_e32 v186, 16, v97
	v_and_b32_e32 v187, 0xffff0000, v97
	v_lshlrev_b32_e32 v190, 16, v98
	v_and_b32_e32 v191, 0xffff0000, v98
	v_lshlrev_b32_e32 v192, 16, v99
	v_and_b32_e32 v193, 0xffff0000, v99
	v_pk_add_f32 v[184:185], v[184:185], v[190:191]
	v_pk_add_f32 v[186:187], v[186:187], v[192:193]
	v_lshlrev_b32_e32 v190, 16, v100
	v_and_b32_e32 v191, 0xffff0000, v100
	v_lshlrev_b32_e32 v192, 16, v101
	v_and_b32_e32 v193, 0xffff0000, v101
	v_pk_add_f32 v[184:185], v[184:185], v[190:191]
	v_pk_add_f32 v[186:187], v[186:187], v[192:193]
	v_lshlrev_b32_e32 v190, 16, v102
	v_and_b32_e32 v191, 0xffff0000, v102
	v_lshlrev_b32_e32 v192, 16, v103
	v_and_b32_e32 v193, 0xffff0000, v103
	v_pk_add_f32 v[184:185], v[184:185], v[190:191]
	v_pk_add_f32 v[186:187], v[186:187], v[192:193]
	v_add_f32_e32 v194, v104, v105
	v_add_f32_e32 v194, v194, v106
	v_add_f32_e32 v194, v194, v107
	v_max_f32_e64 v194, |v194|, 1.0
	v_div_scale_f32 v196, s[52:53], v194, v194, 1.0
	v_rcp_f32_e32 v197, v196
	s_nop 0
	v_fma_f32 v198, -v196, v197, 1.0
	v_fmac_f32_e32 v197, v198, v197
	v_div_scale_f32 v198, vcc, 1.0, v194, 1.0
	v_mul_f32_e32 v199, v198, v197
	v_fma_f32 v195, -v196, v199, v198
	v_fmac_f32_e32 v199, v195, v197
	v_fma_f32 v196, -v196, v199, v198
	v_div_fmas_f32 v196, v196, v197, v199
	v_div_fixup_f32 v195, v196, v194, 1.0
	v_mul_f32_e32 v184, v184, v195
	v_mul_f32_e32 v185, v185, v195
	v_mul_f32_e32 v186, v186, v195
	v_mul_f32_e32 v187, v187, v195
	v_mul_f32_e32 v191, v187, v187
	v_mul_f32_e32 v190, v185, v185
	v_fmac_f32_e32 v190, v184, v184
	v_fmac_f32_e32 v191, v186, v186
	v_add_f32_e32 v188, v190, v191
	s_nop 1
	v_mov_b32_dpp v171, v170 quad_perm:[1,0,3,2] row_mask:0xf bank_mask:0xf
	v_mov_b32_dpp v177, v176 quad_perm:[1,0,3,2] row_mask:0xf bank_mask:0xf
	v_mov_b32_dpp v183, v182 quad_perm:[1,0,3,2] row_mask:0xf bank_mask:0xf
	v_mov_b32_dpp v189, v188 quad_perm:[1,0,3,2] row_mask:0xf bank_mask:0xf
	v_add_f32_e32 v170, v170, v171
	v_add_f32_e32 v176, v176, v177
	v_add_f32_e32 v182, v182, v183
	v_add_f32_e32 v188, v188, v189
	s_nop 1
	v_mov_b32_dpp v171, v170 quad_perm:[2,3,0,1] row_mask:0xf bank_mask:0xf
	v_mov_b32_dpp v177, v176 quad_perm:[2,3,0,1] row_mask:0xf bank_mask:0xf
	v_mov_b32_dpp v183, v182 quad_perm:[2,3,0,1] row_mask:0xf bank_mask:0xf
	v_mov_b32_dpp v189, v188 quad_perm:[2,3,0,1] row_mask:0xf bank_mask:0xf
	v_add_f32_e32 v170, v170, v171
	v_add_f32_e32 v176, v176, v177
	v_add_f32_e32 v182, v182, v183
	v_add_f32_e32 v188, v188, v189
	s_nop 1
	v_mov_b32_dpp v171, v170 row_half_mirror row_mask:0xf bank_mask:0xf
	v_mov_b32_dpp v177, v176 row_half_mirror row_mask:0xf bank_mask:0xf
	v_mov_b32_dpp v183, v182 row_half_mirror row_mask:0xf bank_mask:0xf
	v_mov_b32_dpp v189, v188 row_half_mirror row_mask:0xf bank_mask:0xf
	v_add_f32_e32 v170, v170, v171
	v_add_f32_e32 v176, v176, v177
	v_add_f32_e32 v182, v182, v183
	v_add_f32_e32 v188, v188, v189
	s_nop 1
	v_mov_b32_dpp v171, v170 row_mirror row_mask:0xf bank_mask:0xf
	v_mov_b32_dpp v177, v176 row_mirror row_mask:0xf bank_mask:0xf
	v_mov_b32_dpp v183, v182 row_mirror row_mask:0xf bank_mask:0xf
	v_mov_b32_dpp v189, v188 row_mirror row_mask:0xf bank_mask:0xf
	v_add_f32_e32 v170, v170, v171
	v_add_f32_e32 v176, v176, v177
	v_add_f32_e32 v182, v182, v183
	v_add_f32_e32 v188, v188, v189
	v_mov_b32_e32 v171, v170
	v_mov_b32_e32 v177, v176
	v_mov_b32_e32 v183, v182
	v_mov_b32_e32 v189, v188
	s_nop 1
	v_permlane16_swap_b32 v171, v170
	v_permlane16_swap_b32 v177, v176
	v_permlane16_swap_b32 v183, v182
	v_permlane16_swap_b32 v189, v188
; __device__ __forceinline__ unsigned pk2(float lo, float hi) { f32x2_t v = {lo, hi}; bf16x2_t b = __builtin_convertvector(v, bf16x2_t); return __builtin_bit_cast(unsigned, b); }
; __device__ __forceinline__ float sigmoidf_(float x) { return __builtin_amdgcn_rcpf(1.0f + __expf(-x)); }
; __global__ void __launch_bounds__(NTHREADS, 2) fwd_megakernel(Params P) {
;     ...
;                 const int it = it0 + q * step; const int itc = ok[q] ? it : it0; const int row = itc >> 2, h = itc & 3;
;                 const f32x4 x = v[q] * (1.0f / fmaxf(fabsf(den[q]), 1.0f));
;                 const float ss = wave_sum((x[0] * x[0] + x[1] * x[1]) + (x[2] * x[2] + x[3] * x[3]));
;                 const float rsn = 1.0f / sqrtf(ss * (1.0f / 256.0f) + NORM_EPS);
;                 const f32x4 wn = *(const f32x4*)(q_mnw + l * 1024 + h * 256 + 4 * lane);
;                 u32x2 ow;
;                 ow.x = pk2(x[0] * rsn * wn[0] * sigmoidf_(bflo(mo[q].x)), x[1] * rsn * wn[1] * sigmoidf_(bfhi(mo[q].x)));
;                 ow.y = pk2(x[2] * rsn * wn[2] * sigmoidf_(bflo(mo[q].y)), x[3] * rsn * wn[3] * sigmoidf_(bfhi(mo[q].y)));
;                 if (ok[q]) *(u32x2*)(q_hcat + (size_t)row * 1024 + h * 256 + 4 * lane) = ow;
	v_add_f32_e32 v170, v170, v171
	v_add_f32_e32 v176, v176, v177
	v_add_f32_e32 v182, v182, v183
	v_add_f32_e32 v188, v188, v189
	v_mov_b32_e32 v171, v170
	v_mov_b32_e32 v177, v176
	v_mov_b32_e32 v183, v182
	v_mov_b32_e32 v189, v188
	s_nop 1
	v_permlane32_swap_b32 v171, v170
	v_permlane32_swap_b32 v177, v176
	v_permlane32_swap_b32 v183, v182
	v_permlane32_swap_b32 v189, v188
	v_add_f32_e32 v170, v170, v171
	v_add_f32_e32 v176, v176, v177
	v_add_f32_e32 v182, v182, v183
	v_add_f32_e32 v188, v188, v189
	v_fmamk_f32 v170, v170, 0x3b800000, v214
	v_cmp_gt_f32_e32 vcc, s66, v170
	v_mul_f32_e32 v190, 0x4f800000, v170
	s_nop 0
	v_cndmask_b32_e32 v170, v170, v190, vcc
	v_sqrt_f32_e32 v190, v170
	s_nop 0
	v_add_u32_e32 v191, -1, v190
	v_fma_f32 v192, -v191, v190, v170
	v_cmp_ge_f32_e64 s[40:41], 0, v192
	v_add_u32_e32 v192, 1, v190
	s_nop 0
	v_cndmask_b32_e64 v191, v190, v191, s[40:41]
	v_fma_f32 v190, -v192, v190, v170
	v_cmp_lt_f32_e64 s[40:41], 0, v190
	s_nop 1
	v_cndmask_b32_e64 v190, v191, v192, s[40:41]
	v_mul_f32_e32 v191, 0x37800000, v190
	v_cndmask_b32_e32 v190, v190, v191, vcc
	v_cmp_class_f32_e32 vcc, v170, v215
	s_nop 1
	v_cndmask_b32_e32 v170, v190, v170, vcc
	v_div_scale_f32 v196, s[52:53], v170, v170, 1.0
	v_rcp_f32_e32 v197, v196
	s_nop 0
	v_fma_f32 v198, -v196, v197, 1.0
	v_fmac_f32_e32 v197, v198, v197
	v_div_scale_f32 v198, vcc, 1.0, v170, 1.0
	v_mul_f32_e32 v199, v198, v197
	v_fma_f32 v195, -v196, v199, v198
	v_fmac_f32_e32 v199, v195, v197
	v_fma_f32 v196, -v196, v199, v198
	v_div_fmas_f32 v196, v196, v197, v199
	v_div_fixup_f32 v195, v196, v170, 1.0
	v_mul_f32_e32 v166, v166, v195
	v_mul_f32_e32 v167, v167, v195
	v_mul_f32_e32 v168, v168, v195
	v_mul_f32_e32 v169, v169, v195
	v_mul_f32_e32 v166, v166, v20
	v_mul_f32_e32 v167, v167, v21
	v_mul_f32_e32 v168, v168, v22
	v_mul_f32_e32 v169, v169, v23
	v_lshlrev_b32_e32 v190, 16, v66
	v_and_b32_e32 v191, 0xffff0000, v66
	v_lshlrev_b32_e32 v192, 16, v67
	v_and_b32_e32 v193, 0xffff0000, v67
	v_mul_f32_e32 v190, 0xbfb8aa3b, v190
	v_mul_f32_e32 v191, 0xbfb8aa3b, v191
	v_mul_f32_e32 v192, 0xbfb8aa3b, v192
	v_mul_f32_e32 v193, 0xbfb8aa3b, v193
	v_exp_f32_e32 v190, v190
	v_exp_f32_e32 v191, v191
	v_exp_f32_e32 v192, v192
	v_exp_f32_e32 v193, v193
	v_add_f32_e32 v190, 1.0, v190
	v_add_f32_e32 v191, 1.0, v191
	v_add_f32_e32 v192, 1.0, v192
	v_add_f32_e32 v193, 1.0, v193
	v_rcp_f32_e32 v190, v190
	v_rcp_f32_e32 v191, v191
	v_rcp_f32_e32 v192, v192
	v_rcp_f32_e32 v193, v193
	v_mul_f32_e32 v166, v190, v166
	v_mul_f32_e32 v167, v191, v167
	v_mul_f32_e32 v168, v192, v168
	v_mul_f32_e32 v169, v193, v169
	v_cvt_pk_bf16_f32 v194, v166, v167
	v_cvt_pk_bf16_f32 v195, v168, v169
	global_store_dwordx2 v33, v[194:195], s[38:39]
	v_add_u32_e32 v33, 0x100000, v33
	v_fmamk_f32 v176, v176, 0x3b800000, v214
	v_cmp_gt_f32_e32 vcc, s66, v176
	v_mul_f32_e32 v190, 0x4f800000, v176
	s_nop 0
	v_cndmask_b32_e32 v176, v176, v190, vcc
	v_sqrt_f32_e32 v190, v176
	s_nop 0
	v_add_u32_e32 v191, -1, v190
	v_fma_f32 v192, -v191, v190, v176
	v_cmp_ge_f32_e64 s[40:41], 0, v192
	v_add_u32_e32 v192, 1, v190
	s_nop 0
	v_cndmask_b32_e64 v191, v190, v191, s[40:41]
	v_fma_f32 v190, -v192, v190, v176
	v_cmp_lt_f32_e64 s[40:41], 0, v190
	s_nop 1
	v_cndmask_b32_e64 v190, v191, v192, s[40:41]
	v_mul_f32_e32 v191, 0x37800000, v190
	v_cndmask_b32_e32 v190, v190, v191, vcc
	v_cmp_class_f32_e32 vcc, v176, v215
	s_nop 1
	v_cndmask_b32_e32 v176, v190, v176, vcc
	v_div_scale_f32 v196, s[52:53], v176, v176, 1.0
	v_rcp_f32_e32 v197, v196
	s_nop 0
	v_fma_f32 v198, -v196, v197, 1.0
	v_fmac_f32_e32 v197, v198, v197
	v_div_scale_f32 v198, vcc, 1.0, v176, 1.0
	v_mul_f32_e32 v199, v198, v197
	v_fma_f32 v195, -v196, v199, v198
	v_fmac_f32_e32 v199, v195, v197
	v_fma_f32 v196, -v196, v199, v198
	v_div_fmas_f32 v196, v196, v197, v199
	v_div_fixup_f32 v195, v196, v176, 1.0
	v_mul_f32_e32 v172, v172, v195
	v_mul_f32_e32 v173, v173, v195
	v_mul_f32_e32 v174, v174, v195
	v_mul_f32_e32 v175, v175, v195
	v_mul_f32_e32 v172, v172, v20
	v_mul_f32_e32 v173, v173, v21
	v_mul_f32_e32 v174, v174, v22
	v_mul_f32_e32 v175, v175, v23
	v_lshlrev_b32_e32 v190, 16, v80
	v_and_b32_e32 v191, 0xffff0000, v80
	v_lshlrev_b32_e32 v192, 16, v81
	v_and_b32_e32 v193, 0xffff0000, v81
	v_mul_f32_e32 v190, 0xbfb8aa3b, v190
	v_mul_f32_e32 v191, 0xbfb8aa3b, v191
	v_mul_f32_e32 v192, 0xbfb8aa3b, v192
	v_mul_f32_e32 v193, 0xbfb8aa3b, v193
	v_exp_f32_e32 v190, v190
	v_exp_f32_e32 v191, v191
	v_exp_f32_e32 v192, v192
	v_exp_f32_e32 v193, v193
	v_add_f32_e32 v190, 1.0, v190
	v_add_f32_e32 v191, 1.0, v191
	v_add_f32_e32 v192, 1.0, v192
	v_add_f32_e32 v193, 1.0, v193
	v_rcp_f32_e32 v190, v190
	v_rcp_f32_e32 v191, v191
	v_rcp_f32_e32 v192, v192
	v_rcp_f32_e32 v193, v193
	v_mul_f32_e32 v172, v190, v172
	v_mul_f32_e32 v173, v191, v173
	v_mul_f32_e32 v174, v192, v174
	v_mul_f32_e32 v175, v193, v175
	v_cvt_pk_bf16_f32 v194, v172, v173
	v_cvt_pk_bf16_f32 v195, v174, v175
	global_store_dwordx2 v33, v[194:195], s[38:39]
	v_add_u32_e32 v33, 0x100000, v33
	v_fmamk_f32 v182, v182, 0x3b800000, v214
	v_cmp_gt_f32_e32 vcc, s66, v182
	v_mul_f32_e32 v190, 0x4f800000, v182
	s_nop 0
	v_cndmask_b32_e32 v182, v182, v190, vcc
	v_sqrt_f32_e32 v190, v182
	s_nop 0
	v_add_u32_e32 v191, -1, v190
	v_fma_f32 v192, -v191, v190, v182
	v_cmp_ge_f32_e64 s[40:41], 0, v192
	v_add_u32_e32 v192, 1, v190
	s_nop 0
	v_cndmask_b32_e64 v191, v190, v191, s[40:41]
	v_fma_f32 v190, -v192, v190, v182
	v_cmp_lt_f32_e64 s[40:41], 0, v190
	s_nop 1
	v_cndmask_b32_e64 v190, v191, v192, s[40:41]
	v_mul_f32_e32 v191, 0x37800000, v190
	v_cndmask_b32_e32 v190, v190, v191, vcc
	v_cmp_class_f32_e32 vcc, v182, v215
	s_nop 1
; __device__ __forceinline__ unsigned pk2(float lo, float hi) { f32x2_t v = {lo, hi}; bf16x2_t b = __builtin_convertvector(v, bf16x2_t); return __builtin_bit_cast(unsigned, b); }
; __device__ __forceinline__ float sigmoidf_(float x) { return __builtin_amdgcn_rcpf(1.0f + __expf(-x)); }
; __global__ void __launch_bounds__(NTHREADS, 2) fwd_megakernel(Params P) {
;     ...
;             for (int q = 0; q < 2; ++q) {
;                 const int it = it0 + q * step; ok[q] = it < T * 4; const int itc = ok[q] ? it : it0;
;                 const int row = itc >> 2, h = itc & 3; const size_t o = (size_t)row * 1024 + h * 256 + 4 * lane;
;                 v[q] = (f32x4){0.f, 0.f, 0.f, 0.f}; den[q] = 0.f;
; #pragma unroll
;                 for (int dq = 0; dq < 4; ++dq) { const u32x2 p = *(const u32x2*)(q_mp + (size_t)dq * T * 1024 + o);
;                     v[q][0] += bflo(p.x); v[q][1] += bfhi(p.x); v[q][2] += bflo(p.y); v[q][3] += bfhi(p.y); den[q] += q_dp[(size_t)dq * T * 4 + (size_t)row * 4 + h]; }
;                 mo[q] = *(const u32x2*)(q_proj + (size_t)row * NP + C_MO + h * 256 + 4 * lane);
;     ...
;                 const int it = it0 + q * step; const int itc = ok[q] ? it : it0; const int row = itc >> 2, h = itc & 3;
;                 const f32x4 x = v[q] * (1.0f / fmaxf(fabsf(den[q]), 1.0f));
;                 const float ss = wave_sum((x[0] * x[0] + x[1] * x[1]) + (x[2] * x[2] + x[3] * x[3]));
;                 const float rsn = 1.0f / sqrtf(ss * (1.0f / 256.0f) + NORM_EPS);
;                 const f32x4 wn = *(const f32x4*)(q_mnw + l * 1024 + h * 256 + 4 * lane);
;                 u32x2 ow;
;                 ow.x = pk2(x[0] * rsn * wn[0] * sigmoidf_(bflo(mo[q].x)), x[1] * rsn * wn[1] * sigmoidf_(bfhi(mo[q].x)));
;                 ow.y = pk2(x[2] * rsn * wn[2] * sigmoidf_(bflo(mo[q].y)), x[3] * rsn * wn[3] * sigmoidf_(bfhi(mo[q].y)));
;                 if (ok[q]) *(u32x2*)(q_hcat + (size_t)row * 1024 + h * 256 + 4 * lane) = ow;
	v_cndmask_b32_e32 v182, v190, v182, vcc
	v_div_scale_f32 v196, s[52:53], v182, v182, 1.0
	v_rcp_f32_e32 v197, v196
	s_nop 0
	v_fma_f32 v198, -v196, v197, 1.0
	v_fmac_f32_e32 v197, v198, v197
	v_div_scale_f32 v198, vcc, 1.0, v182, 1.0
	v_mul_f32_e32 v199, v198, v197
	v_fma_f32 v195, -v196, v199, v198
	v_fmac_f32_e32 v199, v195, v197
	v_fma_f32 v196, -v196, v199, v198
	v_div_fmas_f32 v196, v196, v197, v199
	v_div_fixup_f32 v195, v196, v182, 1.0
	v_mul_f32_e32 v178, v178, v195
	v_mul_f32_e32 v179, v179, v195
	v_mul_f32_e32 v180, v180, v195
	v_mul_f32_e32 v181, v181, v195
	v_mul_f32_e32 v178, v178, v20
	v_mul_f32_e32 v179, v179, v21
	v_mul_f32_e32 v180, v180, v22
	v_mul_f32_e32 v181, v181, v23
	v_lshlrev_b32_e32 v190, 16, v94
	v_and_b32_e32 v191, 0xffff0000, v94
	v_lshlrev_b32_e32 v192, 16, v95
	v_and_b32_e32 v193, 0xffff0000, v95
	v_mul_f32_e32 v190, 0xbfb8aa3b, v190
	v_mul_f32_e32 v191, 0xbfb8aa3b, v191
	v_mul_f32_e32 v192, 0xbfb8aa3b, v192
	v_mul_f32_e32 v193, 0xbfb8aa3b, v193
	v_exp_f32_e32 v190, v190
	v_exp_f32_e32 v191, v191
	v_exp_f32_e32 v192, v192
	v_exp_f32_e32 v193, v193
	v_add_f32_e32 v190, 1.0, v190
	v_add_f32_e32 v191, 1.0, v191
	v_add_f32_e32 v192, 1.0, v192
	v_add_f32_e32 v193, 1.0, v193
	v_rcp_f32_e32 v190, v190
	v_rcp_f32_e32 v191, v191
	v_rcp_f32_e32 v192, v192
	v_rcp_f32_e32 v193, v193
	v_mul_f32_e32 v178, v190, v178
	v_mul_f32_e32 v179, v191, v179
	v_mul_f32_e32 v180, v192, v180
	v_mul_f32_e32 v181, v193, v181
	v_cvt_pk_bf16_f32 v194, v178, v179
	v_cvt_pk_bf16_f32 v195, v180, v181
	global_store_dwordx2 v33, v[194:195], s[38:39]
	v_add_u32_e32 v33, 0x100000, v33
	v_fmamk_f32 v188, v188, 0x3b800000, v214
	v_cmp_gt_f32_e32 vcc, s66, v188
	v_mul_f32_e32 v190, 0x4f800000, v188
	s_nop 0
	v_cndmask_b32_e32 v188, v188, v190, vcc
	v_sqrt_f32_e32 v190, v188
	s_nop 0
	v_add_u32_e32 v191, -1, v190
	v_fma_f32 v192, -v191, v190, v188
	v_cmp_ge_f32_e64 s[40:41], 0, v192
	v_add_u32_e32 v192, 1, v190
	s_nop 0
	v_cndmask_b32_e64 v191, v190, v191, s[40:41]
	v_fma_f32 v190, -v192, v190, v188
	v_cmp_lt_f32_e64 s[40:41], 0, v190
	s_nop 1
	v_cndmask_b32_e64 v190, v191, v192, s[40:41]
	v_mul_f32_e32 v191, 0x37800000, v190
	v_cndmask_b32_e32 v190, v190, v191, vcc
	v_cmp_class_f32_e32 vcc, v188, v215
	s_nop 1
	v_cndmask_b32_e32 v188, v190, v188, vcc
	v_div_scale_f32 v196, s[52:53], v188, v188, 1.0
	v_rcp_f32_e32 v197, v196
	s_nop 0
	v_fma_f32 v198, -v196, v197, 1.0
	v_fmac_f32_e32 v197, v198, v197
	v_div_scale_f32 v198, vcc, 1.0, v188, 1.0
	v_mul_f32_e32 v199, v198, v197
	v_fma_f32 v195, -v196, v199, v198
	v_fmac_f32_e32 v199, v195, v197
	v_fma_f32 v196, -v196, v199, v198
	v_div_fmas_f32 v196, v196, v197, v199
	v_div_fixup_f32 v195, v196, v188, 1.0
	v_mul_f32_e32 v184, v184, v195
	v_mul_f32_e32 v185, v185, v195
	v_mul_f32_e32 v186, v186, v195
	v_mul_f32_e32 v187, v187, v195
	v_mul_f32_e32 v184, v184, v20
	v_mul_f32_e32 v185, v185, v21
	v_mul_f32_e32 v186, v186, v22
	v_mul_f32_e32 v187, v187, v23
	v_lshlrev_b32_e32 v190, 16, v108
	v_and_b32_e32 v191, 0xffff0000, v108
	v_lshlrev_b32_e32 v192, 16, v109
	v_and_b32_e32 v193, 0xffff0000, v109
	v_mul_f32_e32 v190, 0xbfb8aa3b, v190
	v_mul_f32_e32 v191, 0xbfb8aa3b, v191
	v_mul_f32_e32 v192, 0xbfb8aa3b, v192
	v_mul_f32_e32 v193, 0xbfb8aa3b, v193
	v_exp_f32_e32 v190, v190
	v_exp_f32_e32 v191, v191
	v_exp_f32_e32 v192, v192
	v_exp_f32_e32 v193, v193
	v_add_f32_e32 v190, 1.0, v190
	v_add_f32_e32 v191, 1.0, v191
	v_add_f32_e32 v192, 1.0, v192
	v_add_f32_e32 v193, 1.0, v193
	v_rcp_f32_e32 v190, v190
	v_rcp_f32_e32 v191, v191
	v_rcp_f32_e32 v192, v192
	v_rcp_f32_e32 v193, v193
	v_mul_f32_e32 v184, v190, v184
	v_mul_f32_e32 v185, v191, v185
	v_mul_f32_e32 v186, v192, v186
	v_mul_f32_e32 v187, v193, v187
	v_cvt_pk_bf16_f32 v194, v184, v185
	v_cvt_pk_bf16_f32 v195, v186, v187
	global_store_dwordx2 v33, v[194:195], s[38:39]
	v_add_u32_e32 v33, 0x100000, v33
	global_load_dwordx2 v[54:55], v15, s[48:49]
	global_load_dwordx2 v[56:57], v15, s[4:5]
	global_load_dwordx2 v[58:59], v15, s[6:7]
	global_load_dwordx2 v[60:61], v15, s[8:9]
	v_add_u32_e32 v24, 0x20000, v16
	v_add_u32_e32 v25, 0x40000, v16
	v_add_u32_e32 v26, 0x60000, v16
	global_load_dword v62, v16, s[50:51]
	global_load_dword v63, v24, s[50:51]
	global_load_dword v64, v25, s[50:51]
	global_load_dword v65, v26, s[50:51]
	global_load_dwordx2 v[66:67], v17, s[34:35]
	v_add_u32_e32 v15, 0x100000, v15
	v_add_u32_e32 v16, 0x2000, v16
	v_add_u32_e32 v17, 0x1100000, v17
	global_load_dwordx2 v[68:69], v15, s[48:49]
	global_load_dwordx2 v[70:71], v15, s[4:5]
	global_load_dwordx2 v[72:73], v15, s[6:7]
	global_load_dwordx2 v[74:75], v15, s[8:9]
	v_add_u32_e32 v24, 0x20000, v16
	v_add_u32_e32 v25, 0x40000, v16
	v_add_u32_e32 v26, 0x60000, v16
	global_load_dword v76, v16, s[50:51]
	global_load_dword v77, v24, s[50:51]
	global_load_dword v78, v25, s[50:51]
	global_load_dword v79, v26, s[50:51]
	global_load_dwordx2 v[80:81], v17, s[34:35]
	v_add_u32_e32 v15, 0x100000, v15
	v_add_u32_e32 v16, 0x2000, v16
	v_add_u32_e32 v17, 0x1100000, v17
	global_load_dwordx2 v[82:83], v15, s[48:49]
	global_load_dwordx2 v[84:85], v15, s[4:5]
	global_load_dwordx2 v[86:87], v15, s[6:7]
	global_load_dwordx2 v[88:89], v15, s[8:9]
	v_add_u32_e32 v24, 0x20000, v16
	v_add_u32_e32 v25, 0x40000, v16
	v_add_u32_e32 v26, 0x60000, v16
	global_load_dword v90, v16, s[50:51]
	global_load_dword v91, v24, s[50:51]
	global_load_dword v92, v25, s[50:51]
	global_load_dword v93, v26, s[50:51]
	global_load_dwordx2 v[94:95], v17, s[34:35]
	v_add_u32_e32 v15, 0x100000, v15
	v_add_u32_e32 v16, 0x2000, v16
	v_add_u32_e32 v17, 0x1100000, v17
	global_load_dwordx2 v[96:97], v15, s[48:49]
	global_load_dwordx2 v[98:99], v15, s[4:5]
	global_load_dwordx2 v[100:101], v15, s[6:7]
	global_load_dwordx2 v[102:103], v15, s[8:9]
	v_add_u32_e32 v24, 0x20000, v16
	v_add_u32_e32 v25, 0x40000, v16
	v_add_u32_e32 v26, 0x60000, v16
	global_load_dword v104, v16, s[50:51]
	global_load_dword v105, v24, s[50:51]
	global_load_dword v106, v25, s[50:51]
	global_load_dword v107, v26, s[50:51]
	global_load_dwordx2 v[108:109], v17, s[34:35]
	v_add_u32_e32 v15, 0x100000, v15
	v_add_u32_e32 v16, 0x2000, v16
	v_add_u32_e32 v17, 0x1100000, v17
	s_waitcnt vmcnt(40)
; __global__ void __launch_bounds__(NTHREADS, 2) fwd_megakernel(Params P) {
;     ...
;                 v[q] = (f32x4){0.f, 0.f, 0.f, 0.f}; den[q] = 0.f;
; #pragma unroll
;                 for (int dq = 0; dq < 4; ++dq) { const u32x2 p = *(const u32x2*)(q_mp + (size_t)dq * T * 1024 + o);
;                     v[q][0] += bflo(p.x); v[q][1] += bfhi(p.x); v[q][2] += bflo(p.y); v[q][3] += bfhi(p.y); den[q] += q_dp[(size_t)dq * T * 4 + (size_t)row * 4 + h]; }
;                 mo[q] = *(const u32x2*)(q_proj + (size_t)row * NP + C_MO + h * 256 + 4 * lane);
;             }
; #pragma unroll
;             for (int q = 0; q < 2; ++q) {
;                 const int it = it0 + q * step; const int itc = ok[q] ? it : it0; const int row = itc >> 2, h = itc & 3;
;                 const f32x4 x = v[q] * (1.0f / fmaxf(fabsf(den[q]), 1.0f));
;                 const float ss = wave_sum((x[0] * x[0] + x[1] * x[1]) + (x[2] * x[2] + x[3] * x[3]));
;                 const float rsn = 1.0f / sqrtf(ss * (1.0f / 256.0f) + NORM_EPS);
	v_lshlrev_b32_e32 v166, 16, v110
	v_and_b32_e32 v167, 0xffff0000, v110
	v_lshlrev_b32_e32 v168, 16, v111
	v_and_b32_e32 v169, 0xffff0000, v111
	v_lshlrev_b32_e32 v190, 16, v112
	v_and_b32_e32 v191, 0xffff0000, v112
	v_lshlrev_b32_e32 v192, 16, v113
	v_and_b32_e32 v193, 0xffff0000, v113
	v_pk_add_f32 v[166:167], v[166:167], v[190:191]
	v_pk_add_f32 v[168:169], v[168:169], v[192:193]
	v_lshlrev_b32_e32 v190, 16, v114
	v_and_b32_e32 v191, 0xffff0000, v114
	v_lshlrev_b32_e32 v192, 16, v115
	v_and_b32_e32 v193, 0xffff0000, v115
	v_pk_add_f32 v[166:167], v[166:167], v[190:191]
	v_pk_add_f32 v[168:169], v[168:169], v[192:193]
	v_lshlrev_b32_e32 v190, 16, v116
	v_and_b32_e32 v191, 0xffff0000, v116
	v_lshlrev_b32_e32 v192, 16, v117
	v_and_b32_e32 v193, 0xffff0000, v117
	v_pk_add_f32 v[166:167], v[166:167], v[190:191]
	v_pk_add_f32 v[168:169], v[168:169], v[192:193]
	v_add_f32_e32 v194, v118, v119
	v_add_f32_e32 v194, v194, v120
	v_add_f32_e32 v194, v194, v121
	v_max_f32_e64 v194, |v194|, 1.0
	v_div_scale_f32 v196, s[52:53], v194, v194, 1.0
	v_rcp_f32_e32 v197, v196
	s_nop 0
	v_fma_f32 v198, -v196, v197, 1.0
	v_fmac_f32_e32 v197, v198, v197
	v_div_scale_f32 v198, vcc, 1.0, v194, 1.0
	v_mul_f32_e32 v199, v198, v197
	v_fma_f32 v195, -v196, v199, v198
	v_fmac_f32_e32 v199, v195, v197
	v_fma_f32 v196, -v196, v199, v198
	v_div_fmas_f32 v196, v196, v197, v199
	v_div_fixup_f32 v195, v196, v194, 1.0
	v_mul_f32_e32 v166, v166, v195
	v_mul_f32_e32 v167, v167, v195
	v_mul_f32_e32 v168, v168, v195
	v_mul_f32_e32 v169, v169, v195
	v_mul_f32_e32 v190, v166, v166
	v_mul_f32_e32 v191, v167, v167
	v_mul_f32_e32 v192, v168, v168
	v_mul_f32_e32 v193, v169, v169
	v_add_f32_e32 v190, v191, v190
	v_add_f32_e32 v192, v192, v193
	v_add_f32_e32 v170, v190, v192
	v_lshlrev_b32_e32 v172, 16, v124
	v_and_b32_e32 v173, 0xffff0000, v124
	v_lshlrev_b32_e32 v174, 16, v125
	v_and_b32_e32 v175, 0xffff0000, v125
	v_lshlrev_b32_e32 v190, 16, v126
	v_and_b32_e32 v191, 0xffff0000, v126
	v_lshlrev_b32_e32 v192, 16, v127
	v_and_b32_e32 v193, 0xffff0000, v127
	v_pk_add_f32 v[172:173], v[172:173], v[190:191]
	v_pk_add_f32 v[174:175], v[174:175], v[192:193]
	v_lshlrev_b32_e32 v190, 16, v128
	v_and_b32_e32 v191, 0xffff0000, v128
	v_lshlrev_b32_e32 v192, 16, v129
	v_and_b32_e32 v193, 0xffff0000, v129
	v_pk_add_f32 v[172:173], v[172:173], v[190:191]
	v_pk_add_f32 v[174:175], v[174:175], v[192:193]
	v_lshlrev_b32_e32 v190, 16, v130
	v_and_b32_e32 v191, 0xffff0000, v130
	v_lshlrev_b32_e32 v192, 16, v131
	v_and_b32_e32 v193, 0xffff0000, v131
	v_pk_add_f32 v[172:173], v[172:173], v[190:191]
	v_pk_add_f32 v[174:175], v[174:175], v[192:193]
	v_add_f32_e32 v194, v132, v133
	v_add_f32_e32 v194, v194, v134
	v_add_f32_e32 v194, v194, v135
	v_max_f32_e64 v194, |v194|, 1.0
	v_div_scale_f32 v196, s[52:53], v194, v194, 1.0
	v_rcp_f32_e32 v197, v196
	s_nop 0
	v_fma_f32 v198, -v196, v197, 1.0
	v_fmac_f32_e32 v197, v198, v197
	v_div_scale_f32 v198, vcc, 1.0, v194, 1.0
	v_mul_f32_e32 v199, v198, v197
	v_fma_f32 v195, -v196, v199, v198
	v_fmac_f32_e32 v199, v195, v197
	v_fma_f32 v196, -v196, v199, v198
	v_div_fmas_f32 v196, v196, v197, v199
	v_div_fixup_f32 v195, v196, v194, 1.0
	v_mul_f32_e32 v172, v172, v195
	v_mul_f32_e32 v173, v173, v195
	v_mul_f32_e32 v174, v174, v195
	v_mul_f32_e32 v175, v175, v195
	v_mul_f32_e32 v191, v175, v175
	v_mul_f32_e32 v190, v173, v173
	v_fmac_f32_e32 v190, v172, v172
	v_fmac_f32_e32 v191, v174, v174
	v_add_f32_e32 v176, v190, v191
	v_lshlrev_b32_e32 v178, 16, v138
	v_and_b32_e32 v179, 0xffff0000, v138
	v_lshlrev_b32_e32 v180, 16, v139
	v_and_b32_e32 v181, 0xffff0000, v139
	v_lshlrev_b32_e32 v190, 16, v140
	v_and_b32_e32 v191, 0xffff0000, v140
	v_lshlrev_b32_e32 v192, 16, v141
	v_and_b32_e32 v193, 0xffff0000, v141
	v_pk_add_f32 v[178:179], v[178:179], v[190:191]
	v_pk_add_f32 v[180:181], v[180:181], v[192:193]
	v_lshlrev_b32_e32 v190, 16, v142
	v_and_b32_e32 v191, 0xffff0000, v142
	v_lshlrev_b32_e32 v192, 16, v143
	v_and_b32_e32 v193, 0xffff0000, v143
	v_pk_add_f32 v[178:179], v[178:179], v[190:191]
	v_pk_add_f32 v[180:181], v[180:181], v[192:193]
	v_lshlrev_b32_e32 v190, 16, v144
	v_and_b32_e32 v191, 0xffff0000, v144
	v_lshlrev_b32_e32 v192, 16, v145
	v_and_b32_e32 v193, 0xffff0000, v145
	v_pk_add_f32 v[178:179], v[178:179], v[190:191]
	v_pk_add_f32 v[180:181], v[180:181], v[192:193]
	v_add_f32_e32 v194, v146, v147
	v_add_f32_e32 v194, v194, v148
	v_add_f32_e32 v194, v194, v149
	v_max_f32_e64 v194, |v194|, 1.0
	v_div_scale_f32 v196, s[52:53], v194, v194, 1.0
	v_rcp_f32_e32 v197, v196
	s_nop 0
	v_fma_f32 v198, -v196, v197, 1.0
	v_fmac_f32_e32 v197, v198, v197
	v_div_scale_f32 v198, vcc, 1.0, v194, 1.0
	v_mul_f32_e32 v199, v198, v197
	v_fma_f32 v195, -v196, v199, v198
	v_fmac_f32_e32 v199, v195, v197
	v_fma_f32 v196, -v196, v199, v198
	v_div_fmas_f32 v196, v196, v197, v199
	v_div_fixup_f32 v195, v196, v194, 1.0
	v_mul_f32_e32 v178, v178, v195
	v_mul_f32_e32 v179, v179, v195
	v_mul_f32_e32 v180, v180, v195
	v_mul_f32_e32 v181, v181, v195
	v_mul_f32_e32 v190, v178, v178
	v_mul_f32_e32 v191, v179, v179
	v_mul_f32_e32 v192, v180, v180
	v_mul_f32_e32 v193, v181, v181
	v_add_f32_e32 v190, v191, v190
	v_add_f32_e32 v192, v192, v193
	v_add_f32_e32 v182, v190, v192
	v_lshlrev_b32_e32 v184, 16, v152
	v_and_b32_e32 v185, 0xffff0000, v152
	v_lshlrev_b32_e32 v186, 16, v153
	v_and_b32_e32 v187, 0xffff0000, v153
	v_lshlrev_b32_e32 v190, 16, v154
	v_and_b32_e32 v191, 0xffff0000, v154
	v_lshlrev_b32_e32 v192, 16, v155
	v_and_b32_e32 v193, 0xffff0000, v155
	v_pk_add_f32 v[184:185], v[184:185], v[190:191]
	v_pk_add_f32 v[186:187], v[186:187], v[192:193]
	v_lshlrev_b32_e32 v190, 16, v156
; __device__ __forceinline__ unsigned pk2(float lo, float hi) { f32x2_t v = {lo, hi}; bf16x2_t b = __builtin_convertvector(v, bf16x2_t); return __builtin_bit_cast(unsigned, b); }
; __device__ __forceinline__ float sigmoidf_(float x) { return __builtin_amdgcn_rcpf(1.0f + __expf(-x)); }
; __global__ void __launch_bounds__(NTHREADS, 2) fwd_megakernel(Params P) {
;     ...
;                 v[q] = (f32x4){0.f, 0.f, 0.f, 0.f}; den[q] = 0.f;
; #pragma unroll
;                 for (int dq = 0; dq < 4; ++dq) { const u32x2 p = *(const u32x2*)(q_mp + (size_t)dq * T * 1024 + o);
;                     v[q][0] += bflo(p.x); v[q][1] += bfhi(p.x); v[q][2] += bflo(p.y); v[q][3] += bfhi(p.y); den[q] += q_dp[(size_t)dq * T * 4 + (size_t)row * 4 + h]; }
;                 mo[q] = *(const u32x2*)(q_proj + (size_t)row * NP + C_MO + h * 256 + 4 * lane);
;             }
; #pragma unroll
;             for (int q = 0; q < 2; ++q) {
;                 const int it = it0 + q * step; const int itc = ok[q] ? it : it0; const int row = itc >> 2, h = itc & 3;
;                 const f32x4 x = v[q] * (1.0f / fmaxf(fabsf(den[q]), 1.0f));
;                 const float ss = wave_sum((x[0] * x[0] + x[1] * x[1]) + (x[2] * x[2] + x[3] * x[3]));
;                 const float rsn = 1.0f / sqrtf(ss * (1.0f / 256.0f) + NORM_EPS);
;                 const f32x4 wn = *(const f32x4*)(q_mnw + l * 1024 + h * 256 + 4 * lane);
;                 u32x2 ow;
;                 ow.x = pk2(x[0] * rsn * wn[0] * sigmoidf_(bflo(mo[q].x)), x[1] * rsn * wn[1] * sigmoidf_(bfhi(mo[q].x)));
;                 ow.y = pk2(x[2] * rsn * wn[2] * sigmoidf_(bflo(mo[q].y)), x[3] * rsn * wn[3] * sigmoidf_(bfhi(mo[q].y)));
;                 if (ok[q]) *(u32x2*)(q_hcat + (size_t)row * 1024 + h * 256 + 4 * lane) = ow;
	v_and_b32_e32 v191, 0xffff0000, v156
	v_lshlrev_b32_e32 v192, 16, v157
	v_and_b32_e32 v193, 0xffff0000, v157
	v_pk_add_f32 v[184:185], v[184:185], v[190:191]
	v_pk_add_f32 v[186:187], v[186:187], v[192:193]
	v_lshlrev_b32_e32 v190, 16, v158
	v_and_b32_e32 v191, 0xffff0000, v158
	v_lshlrev_b32_e32 v192, 16, v159
	v_and_b32_e32 v193, 0xffff0000, v159
	v_pk_add_f32 v[184:185], v[184:185], v[190:191]
	v_pk_add_f32 v[186:187], v[186:187], v[192:193]
	v_add_f32_e32 v194, v160, v161
	v_add_f32_e32 v194, v194, v162
	v_add_f32_e32 v194, v194, v163
	v_max_f32_e64 v194, |v194|, 1.0
	v_div_scale_f32 v196, s[52:53], v194, v194, 1.0
	v_rcp_f32_e32 v197, v196
	s_nop 0
	v_fma_f32 v198, -v196, v197, 1.0
	v_fmac_f32_e32 v197, v198, v197
	v_div_scale_f32 v198, vcc, 1.0, v194, 1.0
	v_mul_f32_e32 v199, v198, v197
	v_fma_f32 v195, -v196, v199, v198
	v_fmac_f32_e32 v199, v195, v197
	v_fma_f32 v196, -v196, v199, v198
	v_div_fmas_f32 v196, v196, v197, v199
	v_div_fixup_f32 v195, v196, v194, 1.0
	v_mul_f32_e32 v184, v184, v195
	v_mul_f32_e32 v185, v185, v195
	v_mul_f32_e32 v186, v186, v195
	v_mul_f32_e32 v187, v187, v195
	v_mul_f32_e32 v191, v187, v187
	v_mul_f32_e32 v190, v185, v185
	v_fmac_f32_e32 v190, v184, v184
	v_fmac_f32_e32 v191, v186, v186
	v_add_f32_e32 v188, v190, v191
	s_nop 1
	v_mov_b32_dpp v171, v170 quad_perm:[1,0,3,2] row_mask:0xf bank_mask:0xf
	v_mov_b32_dpp v177, v176 quad_perm:[1,0,3,2] row_mask:0xf bank_mask:0xf
	v_mov_b32_dpp v183, v182 quad_perm:[1,0,3,2] row_mask:0xf bank_mask:0xf
	v_mov_b32_dpp v189, v188 quad_perm:[1,0,3,2] row_mask:0xf bank_mask:0xf
	v_add_f32_e32 v170, v170, v171
	v_add_f32_e32 v176, v176, v177
	v_add_f32_e32 v182, v182, v183
	v_add_f32_e32 v188, v188, v189
	s_nop 1
	v_mov_b32_dpp v171, v170 quad_perm:[2,3,0,1] row_mask:0xf bank_mask:0xf
	v_mov_b32_dpp v177, v176 quad_perm:[2,3,0,1] row_mask:0xf bank_mask:0xf
	v_mov_b32_dpp v183, v182 quad_perm:[2,3,0,1] row_mask:0xf bank_mask:0xf
	v_mov_b32_dpp v189, v188 quad_perm:[2,3,0,1] row_mask:0xf bank_mask:0xf
	v_add_f32_e32 v170, v170, v171
	v_add_f32_e32 v176, v176, v177
	v_add_f32_e32 v182, v182, v183
	v_add_f32_e32 v188, v188, v189
	s_nop 1
	v_mov_b32_dpp v171, v170 row_half_mirror row_mask:0xf bank_mask:0xf
	v_mov_b32_dpp v177, v176 row_half_mirror row_mask:0xf bank_mask:0xf
	v_mov_b32_dpp v183, v182 row_half_mirror row_mask:0xf bank_mask:0xf
	v_mov_b32_dpp v189, v188 row_half_mirror row_mask:0xf bank_mask:0xf
	v_add_f32_e32 v170, v170, v171
	v_add_f32_e32 v176, v176, v177
	v_add_f32_e32 v182, v182, v183
	v_add_f32_e32 v188, v188, v189
	s_nop 1
	v_mov_b32_dpp v171, v170 row_mirror row_mask:0xf bank_mask:0xf
	v_mov_b32_dpp v177, v176 row_mirror row_mask:0xf bank_mask:0xf
	v_mov_b32_dpp v183, v182 row_mirror row_mask:0xf bank_mask:0xf
	v_mov_b32_dpp v189, v188 row_mirror row_mask:0xf bank_mask:0xf
	v_add_f32_e32 v170, v170, v171
	v_add_f32_e32 v176, v176, v177
	v_add_f32_e32 v182, v182, v183
	v_add_f32_e32 v188, v188, v189
	v_mov_b32_e32 v171, v170
	v_mov_b32_e32 v177, v176
	v_mov_b32_e32 v183, v182
	v_mov_b32_e32 v189, v188
	s_nop 1
	v_permlane16_swap_b32 v171, v170
	v_permlane16_swap_b32 v177, v176
	v_permlane16_swap_b32 v183, v182
	v_permlane16_swap_b32 v189, v188
	v_add_f32_e32 v170, v170, v171
	v_add_f32_e32 v176, v176, v177
	v_add_f32_e32 v182, v182, v183
	v_add_f32_e32 v188, v188, v189
	v_mov_b32_e32 v171, v170
	v_mov_b32_e32 v177, v176
	v_mov_b32_e32 v183, v182
	v_mov_b32_e32 v189, v188
	s_nop 1
	v_permlane32_swap_b32 v171, v170
	v_permlane32_swap_b32 v177, v176
	v_permlane32_swap_b32 v183, v182
	v_permlane32_swap_b32 v189, v188
	v_add_f32_e32 v170, v170, v171
	v_add_f32_e32 v176, v176, v177
	v_add_f32_e32 v182, v182, v183
	v_add_f32_e32 v188, v188, v189
	v_fmamk_f32 v170, v170, 0x3b800000, v214
	v_cmp_gt_f32_e32 vcc, s66, v170
	v_mul_f32_e32 v190, 0x4f800000, v170
	s_nop 0
	v_cndmask_b32_e32 v170, v170, v190, vcc
	v_sqrt_f32_e32 v190, v170
	s_nop 0
	v_add_u32_e32 v191, -1, v190
	v_fma_f32 v192, -v191, v190, v170
	v_cmp_ge_f32_e64 s[40:41], 0, v192
	v_add_u32_e32 v192, 1, v190
	s_nop 0
	v_cndmask_b32_e64 v191, v190, v191, s[40:41]
	v_fma_f32 v190, -v192, v190, v170
	v_cmp_lt_f32_e64 s[40:41], 0, v190
	s_nop 1
	v_cndmask_b32_e64 v190, v191, v192, s[40:41]
	v_mul_f32_e32 v191, 0x37800000, v190
	v_cndmask_b32_e32 v190, v190, v191, vcc
	v_cmp_class_f32_e32 vcc, v170, v215
	s_nop 1
	v_cndmask_b32_e32 v170, v190, v170, vcc
	v_div_scale_f32 v196, s[52:53], v170, v170, 1.0
	v_rcp_f32_e32 v197, v196
	s_nop 0
	v_fma_f32 v198, -v196, v197, 1.0
	v_fmac_f32_e32 v197, v198, v197
	v_div_scale_f32 v198, vcc, 1.0, v170, 1.0
	v_mul_f32_e32 v199, v198, v197
	v_fma_f32 v195, -v196, v199, v198
	v_fmac_f32_e32 v199, v195, v197
	v_fma_f32 v196, -v196, v199, v198
	v_div_fmas_f32 v196, v196, v197, v199
	v_div_fixup_f32 v195, v196, v170, 1.0
	v_mul_f32_e32 v166, v166, v195
	v_mul_f32_e32 v167, v167, v195
	v_mul_f32_e32 v168, v168, v195
	v_mul_f32_e32 v169, v169, v195
	v_mul_f32_e32 v166, v166, v20
	v_mul_f32_e32 v167, v167, v21
	v_mul_f32_e32 v168, v168, v22
	v_mul_f32_e32 v169, v169, v23
	v_lshlrev_b32_e32 v190, 16, v122
	v_and_b32_e32 v191, 0xffff0000, v122
	v_lshlrev_b32_e32 v192, 16, v123
	v_and_b32_e32 v193, 0xffff0000, v123
	v_mul_f32_e32 v190, 0xbfb8aa3b, v190
	v_mul_f32_e32 v191, 0xbfb8aa3b, v191
	v_mul_f32_e32 v192, 0xbfb8aa3b, v192
	v_mul_f32_e32 v193, 0xbfb8aa3b, v193
	v_exp_f32_e32 v190, v190
	v_exp_f32_e32 v191, v191
	v_exp_f32_e32 v192, v192
	v_exp_f32_e32 v193, v193
	v_add_f32_e32 v190, 1.0, v190
	v_add_f32_e32 v191, 1.0, v191
	v_add_f32_e32 v192, 1.0, v192
	v_add_f32_e32 v193, 1.0, v193
	v_rcp_f32_e32 v190, v190
	v_rcp_f32_e32 v191, v191
	v_rcp_f32_e32 v192, v192
; __device__ __forceinline__ unsigned pk2(float lo, float hi) { f32x2_t v = {lo, hi}; bf16x2_t b = __builtin_convertvector(v, bf16x2_t); return __builtin_bit_cast(unsigned, b); }
; __device__ __forceinline__ float sigmoidf_(float x) { return __builtin_amdgcn_rcpf(1.0f + __expf(-x)); }
; __global__ void __launch_bounds__(NTHREADS, 2) fwd_megakernel(Params P) {
;     ...
;                 const f32x4 x = v[q] * (1.0f / fmaxf(fabsf(den[q]), 1.0f));
;                 const float ss = wave_sum((x[0] * x[0] + x[1] * x[1]) + (x[2] * x[2] + x[3] * x[3]));
;                 const float rsn = 1.0f / sqrtf(ss * (1.0f / 256.0f) + NORM_EPS);
;                 const f32x4 wn = *(const f32x4*)(q_mnw + l * 1024 + h * 256 + 4 * lane);
;                 u32x2 ow;
;                 ow.x = pk2(x[0] * rsn * wn[0] * sigmoidf_(bflo(mo[q].x)), x[1] * rsn * wn[1] * sigmoidf_(bfhi(mo[q].x)));
;                 ow.y = pk2(x[2] * rsn * wn[2] * sigmoidf_(bflo(mo[q].y)), x[3] * rsn * wn[3] * sigmoidf_(bfhi(mo[q].y)));
;                 if (ok[q]) *(u32x2*)(q_hcat + (size_t)row * 1024 + h * 256 + 4 * lane) = ow;
	v_rcp_f32_e32 v193, v193
	v_mul_f32_e32 v166, v190, v166
	v_mul_f32_e32 v167, v191, v167
	v_mul_f32_e32 v168, v192, v168
	v_mul_f32_e32 v169, v193, v169
	v_cvt_pk_bf16_f32 v194, v166, v167
	v_cvt_pk_bf16_f32 v195, v168, v169
	global_store_dwordx2 v33, v[194:195], s[38:39]
	v_add_u32_e32 v33, 0x100000, v33
	v_fmamk_f32 v176, v176, 0x3b800000, v214
	v_cmp_gt_f32_e32 vcc, s66, v176
	v_mul_f32_e32 v190, 0x4f800000, v176
	s_nop 0
	v_cndmask_b32_e32 v176, v176, v190, vcc
	v_sqrt_f32_e32 v190, v176
	s_nop 0
	v_add_u32_e32 v191, -1, v190
	v_fma_f32 v192, -v191, v190, v176
	v_cmp_ge_f32_e64 s[40:41], 0, v192
	v_add_u32_e32 v192, 1, v190
	s_nop 0
	v_cndmask_b32_e64 v191, v190, v191, s[40:41]
	v_fma_f32 v190, -v192, v190, v176
	v_cmp_lt_f32_e64 s[40:41], 0, v190
	s_nop 1
	v_cndmask_b32_e64 v190, v191, v192, s[40:41]
	v_mul_f32_e32 v191, 0x37800000, v190
	v_cndmask_b32_e32 v190, v190, v191, vcc
	v_cmp_class_f32_e32 vcc, v176, v215
	s_nop 1
	v_cndmask_b32_e32 v176, v190, v176, vcc
	v_div_scale_f32 v196, s[52:53], v176, v176, 1.0
	v_rcp_f32_e32 v197, v196
	s_nop 0
	v_fma_f32 v198, -v196, v197, 1.0
	v_fmac_f32_e32 v197, v198, v197
	v_div_scale_f32 v198, vcc, 1.0, v176, 1.0
	v_mul_f32_e32 v199, v198, v197
	v_fma_f32 v195, -v196, v199, v198
	v_fmac_f32_e32 v199, v195, v197
	v_fma_f32 v196, -v196, v199, v198
	v_div_fmas_f32 v196, v196, v197, v199
	v_div_fixup_f32 v195, v196, v176, 1.0
	v_mul_f32_e32 v172, v172, v195
	v_mul_f32_e32 v173, v173, v195
	v_mul_f32_e32 v174, v174, v195
	v_mul_f32_e32 v175, v175, v195
	v_mul_f32_e32 v172, v172, v20
	v_mul_f32_e32 v173, v173, v21
	v_mul_f32_e32 v174, v174, v22
	v_mul_f32_e32 v175, v175, v23
	v_lshlrev_b32_e32 v190, 16, v136
	v_and_b32_e32 v191, 0xffff0000, v136
	v_lshlrev_b32_e32 v192, 16, v137
	v_and_b32_e32 v193, 0xffff0000, v137
	v_mul_f32_e32 v190, 0xbfb8aa3b, v190
	v_mul_f32_e32 v191, 0xbfb8aa3b, v191
	v_mul_f32_e32 v192, 0xbfb8aa3b, v192
	v_mul_f32_e32 v193, 0xbfb8aa3b, v193
	v_exp_f32_e32 v190, v190
	v_exp_f32_e32 v191, v191
	v_exp_f32_e32 v192, v192
	v_exp_f32_e32 v193, v193
	v_add_f32_e32 v190, 1.0, v190
	v_add_f32_e32 v191, 1.0, v191
	v_add_f32_e32 v192, 1.0, v192
	v_add_f32_e32 v193, 1.0, v193
	v_rcp_f32_e32 v190, v190
	v_rcp_f32_e32 v191, v191
	v_rcp_f32_e32 v192, v192
	v_rcp_f32_e32 v193, v193
	v_mul_f32_e32 v172, v190, v172
	v_mul_f32_e32 v173, v191, v173
	v_mul_f32_e32 v174, v192, v174
	v_mul_f32_e32 v175, v193, v175
	v_cvt_pk_bf16_f32 v194, v172, v173
	v_cvt_pk_bf16_f32 v195, v174, v175
	global_store_dwordx2 v33, v[194:195], s[38:39]
	v_add_u32_e32 v33, 0x100000, v33
	v_fmamk_f32 v182, v182, 0x3b800000, v214
	v_cmp_gt_f32_e32 vcc, s66, v182
	v_mul_f32_e32 v190, 0x4f800000, v182
	s_nop 0
	v_cndmask_b32_e32 v182, v182, v190, vcc
	v_sqrt_f32_e32 v190, v182
	s_nop 0
	v_add_u32_e32 v191, -1, v190
	v_fma_f32 v192, -v191, v190, v182
	v_cmp_ge_f32_e64 s[40:41], 0, v192
	v_add_u32_e32 v192, 1, v190
	s_nop 0
	v_cndmask_b32_e64 v191, v190, v191, s[40:41]
	v_fma_f32 v190, -v192, v190, v182
	v_cmp_lt_f32_e64 s[40:41], 0, v190
	s_nop 1
	v_cndmask_b32_e64 v190, v191, v192, s[40:41]
	v_mul_f32_e32 v191, 0x37800000, v190
	v_cndmask_b32_e32 v190, v190, v191, vcc
	v_cmp_class_f32_e32 vcc, v182, v215
	s_nop 1
	v_cndmask_b32_e32 v182, v190, v182, vcc
	v_div_scale_f32 v196, s[52:53], v182, v182, 1.0
	v_rcp_f32_e32 v197, v196
	s_nop 0
	v_fma_f32 v198, -v196, v197, 1.0
	v_fmac_f32_e32 v197, v198, v197
	v_div_scale_f32 v198, vcc, 1.0, v182, 1.0
	v_mul_f32_e32 v199, v198, v197
	v_fma_f32 v195, -v196, v199, v198
	v_fmac_f32_e32 v199, v195, v197
	v_fma_f32 v196, -v196, v199, v198
	v_div_fmas_f32 v196, v196, v197, v199
	v_div_fixup_f32 v195, v196, v182, 1.0
	v_mul_f32_e32 v178, v178, v195
	v_mul_f32_e32 v179, v179, v195
	v_mul_f32_e32 v180, v180, v195
	v_mul_f32_e32 v181, v181, v195
	v_mul_f32_e32 v178, v178, v20
	v_mul_f32_e32 v179, v179, v21
	v_mul_f32_e32 v180, v180, v22
	v_mul_f32_e32 v181, v181, v23
	v_lshlrev_b32_e32 v190, 16, v150
	v_and_b32_e32 v191, 0xffff0000, v150
	v_lshlrev_b32_e32 v192, 16, v151
	v_and_b32_e32 v193, 0xffff0000, v151
	v_mul_f32_e32 v190, 0xbfb8aa3b, v190
	v_mul_f32_e32 v191, 0xbfb8aa3b, v191
	v_mul_f32_e32 v192, 0xbfb8aa3b, v192
	v_mul_f32_e32 v193, 0xbfb8aa3b, v193
	v_exp_f32_e32 v190, v190
	v_exp_f32_e32 v191, v191
	v_exp_f32_e32 v192, v192
	v_exp_f32_e32 v193, v193
	v_add_f32_e32 v190, 1.0, v190
	v_add_f32_e32 v191, 1.0, v191
	v_add_f32_e32 v192, 1.0, v192
	v_add_f32_e32 v193, 1.0, v193
	v_rcp_f32_e32 v190, v190
	v_rcp_f32_e32 v191, v191
	v_rcp_f32_e32 v192, v192
	v_rcp_f32_e32 v193, v193
	v_mul_f32_e32 v178, v190, v178
	v_mul_f32_e32 v179, v191, v179
	v_mul_f32_e32 v180, v192, v180
	v_mul_f32_e32 v181, v193, v181
	v_cvt_pk_bf16_f32 v194, v178, v179
	v_cvt_pk_bf16_f32 v195, v180, v181
	global_store_dwordx2 v33, v[194:195], s[38:39]
	v_add_u32_e32 v33, 0x100000, v33
	v_fmamk_f32 v188, v188, 0x3b800000, v214
	v_cmp_gt_f32_e32 vcc, s66, v188
	v_mul_f32_e32 v190, 0x4f800000, v188
	s_nop 0
	v_cndmask_b32_e32 v188, v188, v190, vcc
	v_sqrt_f32_e32 v190, v188
	s_nop 0
	v_add_u32_e32 v191, -1, v190
	v_fma_f32 v192, -v191, v190, v188
	v_cmp_ge_f32_e64 s[40:41], 0, v192
	v_add_u32_e32 v192, 1, v190
	s_nop 0
	v_cndmask_b32_e64 v191, v190, v191, s[40:41]
	v_fma_f32 v190, -v192, v190, v188
	v_cmp_lt_f32_e64 s[40:41], 0, v190
	s_nop 1
	v_cndmask_b32_e64 v190, v191, v192, s[40:41]
	v_mul_f32_e32 v191, 0x37800000, v190
	v_cndmask_b32_e32 v190, v190, v191, vcc
	v_cmp_class_f32_e32 vcc, v188, v215
	s_nop 1
	v_cndmask_b32_e32 v188, v190, v188, vcc
	v_div_scale_f32 v196, s[52:53], v188, v188, 1.0
	v_rcp_f32_e32 v197, v196
	s_nop 0
	v_fma_f32 v198, -v196, v197, 1.0
	v_fmac_f32_e32 v197, v198, v197
; __device__ __forceinline__ unsigned pk2(float lo, float hi) { f32x2_t v = {lo, hi}; bf16x2_t b = __builtin_convertvector(v, bf16x2_t); return __builtin_bit_cast(unsigned, b); }
; __device__ __forceinline__ float sigmoidf_(float x) { return __builtin_amdgcn_rcpf(1.0f + __expf(-x)); }
; __global__ void __launch_bounds__(NTHREADS, 2) fwd_megakernel(Params P) {
;     ...
;             for (int q = 0; q < 2; ++q) {
;                 const int it = it0 + q * step; ok[q] = it < T * 4; const int itc = ok[q] ? it : it0;
;                 const int row = itc >> 2, h = itc & 3; const size_t o = (size_t)row * 1024 + h * 256 + 4 * lane;
;                 v[q] = (f32x4){0.f, 0.f, 0.f, 0.f}; den[q] = 0.f;
; #pragma unroll
;                 for (int dq = 0; dq < 4; ++dq) { const u32x2 p = *(const u32x2*)(q_mp + (size_t)dq * T * 1024 + o);
;                     v[q][0] += bflo(p.x); v[q][1] += bfhi(p.x); v[q][2] += bflo(p.y); v[q][3] += bfhi(p.y); den[q] += q_dp[(size_t)dq * T * 4 + (size_t)row * 4 + h]; }
;                 mo[q] = *(const u32x2*)(q_proj + (size_t)row * NP + C_MO + h * 256 + 4 * lane);
;     ...
;                 const f32x4 x = v[q] * (1.0f / fmaxf(fabsf(den[q]), 1.0f));
;                 const float ss = wave_sum((x[0] * x[0] + x[1] * x[1]) + (x[2] * x[2] + x[3] * x[3]));
;                 const float rsn = 1.0f / sqrtf(ss * (1.0f / 256.0f) + NORM_EPS);
;                 const f32x4 wn = *(const f32x4*)(q_mnw + l * 1024 + h * 256 + 4 * lane);
;                 u32x2 ow;
;                 ow.x = pk2(x[0] * rsn * wn[0] * sigmoidf_(bflo(mo[q].x)), x[1] * rsn * wn[1] * sigmoidf_(bfhi(mo[q].x)));
;                 ow.y = pk2(x[2] * rsn * wn[2] * sigmoidf_(bflo(mo[q].y)), x[3] * rsn * wn[3] * sigmoidf_(bfhi(mo[q].y)));
;                 if (ok[q]) *(u32x2*)(q_hcat + (size_t)row * 1024 + h * 256 + 4 * lane) = ow;
	v_div_scale_f32 v198, vcc, 1.0, v188, 1.0
	v_mul_f32_e32 v199, v198, v197
	v_fma_f32 v195, -v196, v199, v198
	v_fmac_f32_e32 v199, v195, v197
	v_fma_f32 v196, -v196, v199, v198
	v_div_fmas_f32 v196, v196, v197, v199
	v_div_fixup_f32 v195, v196, v188, 1.0
	v_mul_f32_e32 v184, v184, v195
	v_mul_f32_e32 v185, v185, v195
	v_mul_f32_e32 v186, v186, v195
	v_mul_f32_e32 v187, v187, v195
	v_mul_f32_e32 v184, v184, v20
	v_mul_f32_e32 v185, v185, v21
	v_mul_f32_e32 v186, v186, v22
	v_mul_f32_e32 v187, v187, v23
	v_lshlrev_b32_e32 v190, 16, v164
	v_and_b32_e32 v191, 0xffff0000, v164
	v_lshlrev_b32_e32 v192, 16, v165
	v_and_b32_e32 v193, 0xffff0000, v165
	v_mul_f32_e32 v190, 0xbfb8aa3b, v190
	v_mul_f32_e32 v191, 0xbfb8aa3b, v191
	v_mul_f32_e32 v192, 0xbfb8aa3b, v192
	v_mul_f32_e32 v193, 0xbfb8aa3b, v193
	v_exp_f32_e32 v190, v190
	v_exp_f32_e32 v191, v191
	v_exp_f32_e32 v192, v192
	v_exp_f32_e32 v193, v193
	v_add_f32_e32 v190, 1.0, v190
	v_add_f32_e32 v191, 1.0, v191
	v_add_f32_e32 v192, 1.0, v192
	v_add_f32_e32 v193, 1.0, v193
	v_rcp_f32_e32 v190, v190
	v_rcp_f32_e32 v191, v191
	v_rcp_f32_e32 v192, v192
	v_rcp_f32_e32 v193, v193
	v_mul_f32_e32 v184, v190, v184
	v_mul_f32_e32 v185, v191, v185
	v_mul_f32_e32 v186, v192, v186
	v_mul_f32_e32 v187, v193, v187
	v_cvt_pk_bf16_f32 v194, v184, v185
	v_cvt_pk_bf16_f32 v195, v186, v187
	global_store_dwordx2 v33, v[194:195], s[38:39]
	v_add_u32_e32 v33, 0x100000, v33
	global_load_dwordx2 v[110:111], v15, s[48:49]
	global_load_dwordx2 v[112:113], v15, s[4:5]
	global_load_dwordx2 v[114:115], v15, s[6:7]
	global_load_dwordx2 v[116:117], v15, s[8:9]
	v_add_u32_e32 v24, 0x20000, v16
	v_add_u32_e32 v25, 0x40000, v16
	v_add_u32_e32 v26, 0x60000, v16
	global_load_dword v118, v16, s[50:51]
	global_load_dword v119, v24, s[50:51]
	global_load_dword v120, v25, s[50:51]
	global_load_dword v121, v26, s[50:51]
	global_load_dwordx2 v[122:123], v17, s[34:35]
	v_add_u32_e32 v15, 0x100000, v15
	v_add_u32_e32 v16, 0x2000, v16
	v_add_u32_e32 v17, 0x1100000, v17
	global_load_dwordx2 v[124:125], v15, s[48:49]
	global_load_dwordx2 v[126:127], v15, s[4:5]
	global_load_dwordx2 v[128:129], v15, s[6:7]
	global_load_dwordx2 v[130:131], v15, s[8:9]
	v_add_u32_e32 v24, 0x20000, v16
	v_add_u32_e32 v25, 0x40000, v16
	v_add_u32_e32 v26, 0x60000, v16
	global_load_dword v132, v16, s[50:51]
	global_load_dword v133, v24, s[50:51]
	global_load_dword v134, v25, s[50:51]
	global_load_dword v135, v26, s[50:51]
	global_load_dwordx2 v[136:137], v17, s[34:35]
	v_add_u32_e32 v15, 0x100000, v15
	v_add_u32_e32 v16, 0x2000, v16
	v_add_u32_e32 v17, 0x1100000, v17
	global_load_dwordx2 v[138:139], v15, s[48:49]
	global_load_dwordx2 v[140:141], v15, s[4:5]
	global_load_dwordx2 v[142:143], v15, s[6:7]
	global_load_dwordx2 v[144:145], v15, s[8:9]
	v_add_u32_e32 v24, 0x20000, v16
	v_add_u32_e32 v25, 0x40000, v16
	v_add_u32_e32 v26, 0x60000, v16
	global_load_dword v146, v16, s[50:51]
	global_load_dword v147, v24, s[50:51]
	global_load_dword v148, v25, s[50:51]
	global_load_dword v149, v26, s[50:51]
	global_load_dwordx2 v[150:151], v17, s[34:35]
	v_add_u32_e32 v15, 0x100000, v15
	v_add_u32_e32 v16, 0x2000, v16
	v_add_u32_e32 v17, 0x1100000, v17
	global_load_dwordx2 v[152:153], v15, s[48:49]
	global_load_dwordx2 v[154:155], v15, s[4:5]
	global_load_dwordx2 v[156:157], v15, s[6:7]
	global_load_dwordx2 v[158:159], v15, s[8:9]
	v_add_u32_e32 v24, 0x20000, v16
	v_add_u32_e32 v25, 0x40000, v16
	v_add_u32_e32 v26, 0x60000, v16
	global_load_dword v160, v16, s[50:51]
	global_load_dword v161, v24, s[50:51]
	global_load_dword v162, v25, s[50:51]
	global_load_dword v163, v26, s[50:51]
	global_load_dwordx2 v[164:165], v17, s[34:35]
	v_add_u32_e32 v15, 0x100000, v15
	v_add_u32_e32 v16, 0x2000, v16
	v_add_u32_e32 v17, 0x1100000, v17
	s_waitcnt vmcnt(40)
	v_lshlrev_b32_e32 v166, 16, v54
	v_and_b32_e32 v167, 0xffff0000, v54
	v_lshlrev_b32_e32 v168, 16, v55
	v_and_b32_e32 v169, 0xffff0000, v55
	v_lshlrev_b32_e32 v190, 16, v56
	v_and_b32_e32 v191, 0xffff0000, v56
	v_lshlrev_b32_e32 v192, 16, v57
	v_and_b32_e32 v193, 0xffff0000, v57
	v_pk_add_f32 v[166:167], v[166:167], v[190:191]
	v_pk_add_f32 v[168:169], v[168:169], v[192:193]
	v_lshlrev_b32_e32 v190, 16, v58
	v_and_b32_e32 v191, 0xffff0000, v58
	v_lshlrev_b32_e32 v192, 16, v59
	v_and_b32_e32 v193, 0xffff0000, v59
	v_pk_add_f32 v[166:167], v[166:167], v[190:191]
	v_pk_add_f32 v[168:169], v[168:169], v[192:193]
	v_lshlrev_b32_e32 v190, 16, v60
	v_and_b32_e32 v191, 0xffff0000, v60
	v_lshlrev_b32_e32 v192, 16, v61
	v_and_b32_e32 v193, 0xffff0000, v61
	v_pk_add_f32 v[166:167], v[166:167], v[190:191]
	v_pk_add_f32 v[168:169], v[168:169], v[192:193]
	v_add_f32_e32 v194, v62, v63
	v_add_f32_e32 v194, v194, v64
	v_add_f32_e32 v194, v194, v65
	v_max_f32_e64 v194, |v194|, 1.0
	v_div_scale_f32 v196, s[52:53], v194, v194, 1.0
	v_rcp_f32_e32 v197, v196
	s_nop 0
	v_fma_f32 v198, -v196, v197, 1.0
	v_fmac_f32_e32 v197, v198, v197
	v_div_scale_f32 v198, vcc, 1.0, v194, 1.0
	v_mul_f32_e32 v199, v198, v197
	v_fma_f32 v195, -v196, v199, v198
	v_fmac_f32_e32 v199, v195, v197
	v_fma_f32 v196, -v196, v199, v198
	v_div_fmas_f32 v196, v196, v197, v199
	v_div_fixup_f32 v195, v196, v194, 1.0
	v_mul_f32_e32 v166, v166, v195
	v_mul_f32_e32 v167, v167, v195
	v_mul_f32_e32 v168, v168, v195
	v_mul_f32_e32 v169, v169, v195
	v_mul_f32_e32 v190, v166, v166
	v_mul_f32_e32 v191, v167, v167
	v_mul_f32_e32 v192, v168, v168
	v_mul_f32_e32 v193, v169, v169
	v_add_f32_e32 v190, v191, v190
	v_add_f32_e32 v192, v192, v193
	v_add_f32_e32 v170, v190, v192
	v_lshlrev_b32_e32 v172, 16, v68
	v_and_b32_e32 v173, 0xffff0000, v68
	v_lshlrev_b32_e32 v174, 16, v69
	v_and_b32_e32 v175, 0xffff0000, v69
; __global__ void __launch_bounds__(NTHREADS, 2) fwd_megakernel(Params P) {
;     ...
;                 v[q] = (f32x4){0.f, 0.f, 0.f, 0.f}; den[q] = 0.f;
; #pragma unroll
;                 for (int dq = 0; dq < 4; ++dq) { const u32x2 p = *(const u32x2*)(q_mp + (size_t)dq * T * 1024 + o);
;                     v[q][0] += bflo(p.x); v[q][1] += bfhi(p.x); v[q][2] += bflo(p.y); v[q][3] += bfhi(p.y); den[q] += q_dp[(size_t)dq * T * 4 + (size_t)row * 4 + h]; }
;                 mo[q] = *(const u32x2*)(q_proj + (size_t)row * NP + C_MO + h * 256 + 4 * lane);
;             }
; #pragma unroll
;             for (int q = 0; q < 2; ++q) {
;                 const int it = it0 + q * step; const int itc = ok[q] ? it : it0; const int row = itc >> 2, h = itc & 3;
;                 const f32x4 x = v[q] * (1.0f / fmaxf(fabsf(den[q]), 1.0f));
;                 const float ss = wave_sum((x[0] * x[0] + x[1] * x[1]) + (x[2] * x[2] + x[3] * x[3]));
;                 const float rsn = 1.0f / sqrtf(ss * (1.0f / 256.0f) + NORM_EPS);
	v_lshlrev_b32_e32 v190, 16, v70
	v_and_b32_e32 v191, 0xffff0000, v70
	v_lshlrev_b32_e32 v192, 16, v71
	v_and_b32_e32 v193, 0xffff0000, v71
	v_pk_add_f32 v[172:173], v[172:173], v[190:191]
	v_pk_add_f32 v[174:175], v[174:175], v[192:193]
	v_lshlrev_b32_e32 v190, 16, v72
	v_and_b32_e32 v191, 0xffff0000, v72
	v_lshlrev_b32_e32 v192, 16, v73
	v_and_b32_e32 v193, 0xffff0000, v73
	v_pk_add_f32 v[172:173], v[172:173], v[190:191]
	v_pk_add_f32 v[174:175], v[174:175], v[192:193]
	v_lshlrev_b32_e32 v190, 16, v74
	v_and_b32_e32 v191, 0xffff0000, v74
	v_lshlrev_b32_e32 v192, 16, v75
	v_and_b32_e32 v193, 0xffff0000, v75
	v_pk_add_f32 v[172:173], v[172:173], v[190:191]
	v_pk_add_f32 v[174:175], v[174:175], v[192:193]
	v_add_f32_e32 v194, v76, v77
	v_add_f32_e32 v194, v194, v78
	v_add_f32_e32 v194, v194, v79
	v_max_f32_e64 v194, |v194|, 1.0
	v_div_scale_f32 v196, s[52:53], v194, v194, 1.0
	v_rcp_f32_e32 v197, v196
	s_nop 0
	v_fma_f32 v198, -v196, v197, 1.0
	v_fmac_f32_e32 v197, v198, v197
	v_div_scale_f32 v198, vcc, 1.0, v194, 1.0
	v_mul_f32_e32 v199, v198, v197
	v_fma_f32 v195, -v196, v199, v198
	v_fmac_f32_e32 v199, v195, v197
	v_fma_f32 v196, -v196, v199, v198
	v_div_fmas_f32 v196, v196, v197, v199
	v_div_fixup_f32 v195, v196, v194, 1.0
	v_mul_f32_e32 v172, v172, v195
	v_mul_f32_e32 v173, v173, v195
	v_mul_f32_e32 v174, v174, v195
	v_mul_f32_e32 v175, v175, v195
	v_mul_f32_e32 v191, v175, v175
	v_mul_f32_e32 v190, v173, v173
	v_fmac_f32_e32 v190, v172, v172
	v_fmac_f32_e32 v191, v174, v174
	v_add_f32_e32 v176, v190, v191
	v_lshlrev_b32_e32 v178, 16, v82
	v_and_b32_e32 v179, 0xffff0000, v82
	v_lshlrev_b32_e32 v180, 16, v83
	v_and_b32_e32 v181, 0xffff0000, v83
	v_lshlrev_b32_e32 v190, 16, v84
	v_and_b32_e32 v191, 0xffff0000, v84
	v_lshlrev_b32_e32 v192, 16, v85
	v_and_b32_e32 v193, 0xffff0000, v85
	v_pk_add_f32 v[178:179], v[178:179], v[190:191]
	v_pk_add_f32 v[180:181], v[180:181], v[192:193]
	v_lshlrev_b32_e32 v190, 16, v86
	v_and_b32_e32 v191, 0xffff0000, v86
	v_lshlrev_b32_e32 v192, 16, v87
	v_and_b32_e32 v193, 0xffff0000, v87
	v_pk_add_f32 v[178:179], v[178:179], v[190:191]
	v_pk_add_f32 v[180:181], v[180:181], v[192:193]
	v_lshlrev_b32_e32 v190, 16, v88
	v_and_b32_e32 v191, 0xffff0000, v88
	v_lshlrev_b32_e32 v192, 16, v89
	v_and_b32_e32 v193, 0xffff0000, v89
	v_pk_add_f32 v[178:179], v[178:179], v[190:191]
	v_pk_add_f32 v[180:181], v[180:181], v[192:193]
	v_add_f32_e32 v194, v90, v91
	v_add_f32_e32 v194, v194, v92
	v_add_f32_e32 v194, v194, v93
	v_max_f32_e64 v194, |v194|, 1.0
	v_div_scale_f32 v196, s[52:53], v194, v194, 1.0
	v_rcp_f32_e32 v197, v196
	s_nop 0
	v_fma_f32 v198, -v196, v197, 1.0
	v_fmac_f32_e32 v197, v198, v197
	v_div_scale_f32 v198, vcc, 1.0, v194, 1.0
	v_mul_f32_e32 v199, v198, v197
	v_fma_f32 v195, -v196, v199, v198
	v_fmac_f32_e32 v199, v195, v197
	v_fma_f32 v196, -v196, v199, v198
	v_div_fmas_f32 v196, v196, v197, v199
	v_div_fixup_f32 v195, v196, v194, 1.0
	v_mul_f32_e32 v178, v178, v195
	v_mul_f32_e32 v179, v179, v195
	v_mul_f32_e32 v180, v180, v195
	v_mul_f32_e32 v181, v181, v195
	v_mul_f32_e32 v190, v178, v178
	v_mul_f32_e32 v191, v179, v179
	v_mul_f32_e32 v192, v180, v180
	v_mul_f32_e32 v193, v181, v181
	v_add_f32_e32 v190, v191, v190
	v_add_f32_e32 v192, v192, v193
	v_add_f32_e32 v182, v190, v192
	v_lshlrev_b32_e32 v184, 16, v96
	v_and_b32_e32 v185, 0xffff0000, v96
	v_lshlrev_b32_e32 v186, 16, v97
	v_and_b32_e32 v187, 0xffff0000, v97
	v_lshlrev_b32_e32 v190, 16, v98
	v_and_b32_e32 v191, 0xffff0000, v98
	v_lshlrev_b32_e32 v192, 16, v99
	v_and_b32_e32 v193, 0xffff0000, v99
	v_pk_add_f32 v[184:185], v[184:185], v[190:191]
	v_pk_add_f32 v[186:187], v[186:187], v[192:193]
	v_lshlrev_b32_e32 v190, 16, v100
	v_and_b32_e32 v191, 0xffff0000, v100
	v_lshlrev_b32_e32 v192, 16, v101
	v_and_b32_e32 v193, 0xffff0000, v101
	v_pk_add_f32 v[184:185], v[184:185], v[190:191]
	v_pk_add_f32 v[186:187], v[186:187], v[192:193]
	v_lshlrev_b32_e32 v190, 16, v102
	v_and_b32_e32 v191, 0xffff0000, v102
	v_lshlrev_b32_e32 v192, 16, v103
	v_and_b32_e32 v193, 0xffff0000, v103
	v_pk_add_f32 v[184:185], v[184:185], v[190:191]
	v_pk_add_f32 v[186:187], v[186:187], v[192:193]
	v_add_f32_e32 v194, v104, v105
	v_add_f32_e32 v194, v194, v106
	v_add_f32_e32 v194, v194, v107
	v_max_f32_e64 v194, |v194|, 1.0
	v_div_scale_f32 v196, s[52:53], v194, v194, 1.0
	v_rcp_f32_e32 v197, v196
	s_nop 0
	v_fma_f32 v198, -v196, v197, 1.0
	v_fmac_f32_e32 v197, v198, v197
	v_div_scale_f32 v198, vcc, 1.0, v194, 1.0
	v_mul_f32_e32 v199, v198, v197
	v_fma_f32 v195, -v196, v199, v198
	v_fmac_f32_e32 v199, v195, v197
	v_fma_f32 v196, -v196, v199, v198
	v_div_fmas_f32 v196, v196, v197, v199
	v_div_fixup_f32 v195, v196, v194, 1.0
	v_mul_f32_e32 v184, v184, v195
	v_mul_f32_e32 v185, v185, v195
	v_mul_f32_e32 v186, v186, v195
	v_mul_f32_e32 v187, v187, v195
	v_mul_f32_e32 v191, v187, v187
	v_mul_f32_e32 v190, v185, v185
	v_fmac_f32_e32 v190, v184, v184
	v_fmac_f32_e32 v191, v186, v186
	v_add_f32_e32 v188, v190, v191
	s_nop 1
	v_mov_b32_dpp v171, v170 quad_perm:[1,0,3,2] row_mask:0xf bank_mask:0xf
	v_mov_b32_dpp v177, v176 quad_perm:[1,0,3,2] row_mask:0xf bank_mask:0xf
	v_mov_b32_dpp v183, v182 quad_perm:[1,0,3,2] row_mask:0xf bank_mask:0xf
	v_mov_b32_dpp v189, v188 quad_perm:[1,0,3,2] row_mask:0xf bank_mask:0xf
	v_add_f32_e32 v170, v170, v171
	v_add_f32_e32 v176, v176, v177
	v_add_f32_e32 v182, v182, v183
	v_add_f32_e32 v188, v188, v189
	s_nop 1
	v_mov_b32_dpp v171, v170 quad_perm:[2,3,0,1] row_mask:0xf bank_mask:0xf
	v_mov_b32_dpp v177, v176 quad_perm:[2,3,0,1] row_mask:0xf bank_mask:0xf
	v_mov_b32_dpp v183, v182 quad_perm:[2,3,0,1] row_mask:0xf bank_mask:0xf
; __device__ __forceinline__ unsigned pk2(float lo, float hi) { f32x2_t v = {lo, hi}; bf16x2_t b = __builtin_convertvector(v, bf16x2_t); return __builtin_bit_cast(unsigned, b); }
; __device__ __forceinline__ float sigmoidf_(float x) { return __builtin_amdgcn_rcpf(1.0f + __expf(-x)); }
; __global__ void __launch_bounds__(NTHREADS, 2) fwd_megakernel(Params P) {
;     ...
;                 const float ss = wave_sum((x[0] * x[0] + x[1] * x[1]) + (x[2] * x[2] + x[3] * x[3]));
;                 const float rsn = 1.0f / sqrtf(ss * (1.0f / 256.0f) + NORM_EPS);
;                 const f32x4 wn = *(const f32x4*)(q_mnw + l * 1024 + h * 256 + 4 * lane);
;                 u32x2 ow;
;                 ow.x = pk2(x[0] * rsn * wn[0] * sigmoidf_(bflo(mo[q].x)), x[1] * rsn * wn[1] * sigmoidf_(bfhi(mo[q].x)));
;                 ow.y = pk2(x[2] * rsn * wn[2] * sigmoidf_(bflo(mo[q].y)), x[3] * rsn * wn[3] * sigmoidf_(bfhi(mo[q].y)));
;                 if (ok[q]) *(u32x2*)(q_hcat + (size_t)row * 1024 + h * 256 + 4 * lane) = ow;
	v_mov_b32_dpp v189, v188 quad_perm:[2,3,0,1] row_mask:0xf bank_mask:0xf
	v_add_f32_e32 v170, v170, v171
	v_add_f32_e32 v176, v176, v177
	v_add_f32_e32 v182, v182, v183
	v_add_f32_e32 v188, v188, v189
	s_nop 1
	v_mov_b32_dpp v171, v170 row_half_mirror row_mask:0xf bank_mask:0xf
	v_mov_b32_dpp v177, v176 row_half_mirror row_mask:0xf bank_mask:0xf
	v_mov_b32_dpp v183, v182 row_half_mirror row_mask:0xf bank_mask:0xf
	v_mov_b32_dpp v189, v188 row_half_mirror row_mask:0xf bank_mask:0xf
	v_add_f32_e32 v170, v170, v171
	v_add_f32_e32 v176, v176, v177
	v_add_f32_e32 v182, v182, v183
	v_add_f32_e32 v188, v188, v189
	s_nop 1
	v_mov_b32_dpp v171, v170 row_mirror row_mask:0xf bank_mask:0xf
	v_mov_b32_dpp v177, v176 row_mirror row_mask:0xf bank_mask:0xf
	v_mov_b32_dpp v183, v182 row_mirror row_mask:0xf bank_mask:0xf
	v_mov_b32_dpp v189, v188 row_mirror row_mask:0xf bank_mask:0xf
	v_add_f32_e32 v170, v170, v171
	v_add_f32_e32 v176, v176, v177
	v_add_f32_e32 v182, v182, v183
	v_add_f32_e32 v188, v188, v189
	v_mov_b32_e32 v171, v170
	v_mov_b32_e32 v177, v176
	v_mov_b32_e32 v183, v182
	v_mov_b32_e32 v189, v188
	s_nop 1
	v_permlane16_swap_b32 v171, v170
	v_permlane16_swap_b32 v177, v176
	v_permlane16_swap_b32 v183, v182
	v_permlane16_swap_b32 v189, v188
	v_add_f32_e32 v170, v170, v171
	v_add_f32_e32 v176, v176, v177
	v_add_f32_e32 v182, v182, v183
	v_add_f32_e32 v188, v188, v189
	v_mov_b32_e32 v171, v170
	v_mov_b32_e32 v177, v176
	v_mov_b32_e32 v183, v182
	v_mov_b32_e32 v189, v188
	s_nop 1
	v_permlane32_swap_b32 v171, v170
	v_permlane32_swap_b32 v177, v176
	v_permlane32_swap_b32 v183, v182
	v_permlane32_swap_b32 v189, v188
	v_add_f32_e32 v170, v170, v171
	v_add_f32_e32 v176, v176, v177
	v_add_f32_e32 v182, v182, v183
	v_add_f32_e32 v188, v188, v189
	v_fmamk_f32 v170, v170, 0x3b800000, v214
	v_cmp_gt_f32_e32 vcc, s66, v170
	v_mul_f32_e32 v190, 0x4f800000, v170
	s_nop 0
	v_cndmask_b32_e32 v170, v170, v190, vcc
	v_sqrt_f32_e32 v190, v170
	s_nop 0
	v_add_u32_e32 v191, -1, v190
	v_fma_f32 v192, -v191, v190, v170
	v_cmp_ge_f32_e64 s[40:41], 0, v192
	v_add_u32_e32 v192, 1, v190
	s_nop 0
	v_cndmask_b32_e64 v191, v190, v191, s[40:41]
	v_fma_f32 v190, -v192, v190, v170
	v_cmp_lt_f32_e64 s[40:41], 0, v190
	s_nop 1
	v_cndmask_b32_e64 v190, v191, v192, s[40:41]
	v_mul_f32_e32 v191, 0x37800000, v190
	v_cndmask_b32_e32 v190, v190, v191, vcc
	v_cmp_class_f32_e32 vcc, v170, v215
	s_nop 1
	v_cndmask_b32_e32 v170, v190, v170, vcc
	v_div_scale_f32 v196, s[52:53], v170, v170, 1.0
	v_rcp_f32_e32 v197, v196
	s_nop 0
	v_fma_f32 v198, -v196, v197, 1.0
	v_fmac_f32_e32 v197, v198, v197
	v_div_scale_f32 v198, vcc, 1.0, v170, 1.0
	v_mul_f32_e32 v199, v198, v197
	v_fma_f32 v195, -v196, v199, v198
	v_fmac_f32_e32 v199, v195, v197
	v_fma_f32 v196, -v196, v199, v198
	v_div_fmas_f32 v196, v196, v197, v199
	v_div_fixup_f32 v195, v196, v170, 1.0
	v_mul_f32_e32 v166, v166, v195
	v_mul_f32_e32 v167, v167, v195
	v_mul_f32_e32 v168, v168, v195
	v_mul_f32_e32 v169, v169, v195
	v_mul_f32_e32 v166, v166, v20
	v_mul_f32_e32 v167, v167, v21
	v_mul_f32_e32 v168, v168, v22
	v_mul_f32_e32 v169, v169, v23
	v_lshlrev_b32_e32 v190, 16, v66
	v_and_b32_e32 v191, 0xffff0000, v66
	v_lshlrev_b32_e32 v192, 16, v67
	v_and_b32_e32 v193, 0xffff0000, v67
	v_mul_f32_e32 v190, 0xbfb8aa3b, v190
	v_mul_f32_e32 v191, 0xbfb8aa3b, v191
	v_mul_f32_e32 v192, 0xbfb8aa3b, v192
	v_mul_f32_e32 v193, 0xbfb8aa3b, v193
	v_exp_f32_e32 v190, v190
	v_exp_f32_e32 v191, v191
	v_exp_f32_e32 v192, v192
	v_exp_f32_e32 v193, v193
	v_add_f32_e32 v190, 1.0, v190
	v_add_f32_e32 v191, 1.0, v191
	v_add_f32_e32 v192, 1.0, v192
	v_add_f32_e32 v193, 1.0, v193
	v_rcp_f32_e32 v190, v190
	v_rcp_f32_e32 v191, v191
	v_rcp_f32_e32 v192, v192
	v_rcp_f32_e32 v193, v193
	v_mul_f32_e32 v166, v190, v166
	v_mul_f32_e32 v167, v191, v167
	v_mul_f32_e32 v168, v192, v168
	v_mul_f32_e32 v169, v193, v169
	v_cvt_pk_bf16_f32 v194, v166, v167
	v_cvt_pk_bf16_f32 v195, v168, v169
	global_store_dwordx2 v33, v[194:195], s[38:39]
	v_add_u32_e32 v33, 0x100000, v33
	v_fmamk_f32 v176, v176, 0x3b800000, v214
	v_cmp_gt_f32_e32 vcc, s66, v176
	v_mul_f32_e32 v190, 0x4f800000, v176
	s_nop 0
	v_cndmask_b32_e32 v176, v176, v190, vcc
	v_sqrt_f32_e32 v190, v176
	s_nop 0
	v_add_u32_e32 v191, -1, v190
	v_fma_f32 v192, -v191, v190, v176
	v_cmp_ge_f32_e64 s[40:41], 0, v192
	v_add_u32_e32 v192, 1, v190
	s_nop 0
	v_cndmask_b32_e64 v191, v190, v191, s[40:41]
	v_fma_f32 v190, -v192, v190, v176
	v_cmp_lt_f32_e64 s[40:41], 0, v190
	s_nop 1
	v_cndmask_b32_e64 v190, v191, v192, s[40:41]
	v_mul_f32_e32 v191, 0x37800000, v190
	v_cndmask_b32_e32 v190, v190, v191, vcc
	v_cmp_class_f32_e32 vcc, v176, v215
	s_nop 1
	v_cndmask_b32_e32 v176, v190, v176, vcc
	v_div_scale_f32 v196, s[52:53], v176, v176, 1.0
	v_rcp_f32_e32 v197, v196
	s_nop 0
	v_fma_f32 v198, -v196, v197, 1.0
	v_fmac_f32_e32 v197, v198, v197
	v_div_scale_f32 v198, vcc, 1.0, v176, 1.0
	v_mul_f32_e32 v199, v198, v197
	v_fma_f32 v195, -v196, v199, v198
	v_fmac_f32_e32 v199, v195, v197
	v_fma_f32 v196, -v196, v199, v198
	v_div_fmas_f32 v196, v196, v197, v199
	v_div_fixup_f32 v195, v196, v176, 1.0
	v_mul_f32_e32 v172, v172, v195
	v_mul_f32_e32 v173, v173, v195
	v_mul_f32_e32 v174, v174, v195
	v_mul_f32_e32 v175, v175, v195
	v_mul_f32_e32 v172, v172, v20
	v_mul_f32_e32 v173, v173, v21
	v_mul_f32_e32 v174, v174, v22
	v_mul_f32_e32 v175, v175, v23
	v_lshlrev_b32_e32 v190, 16, v80
	v_and_b32_e32 v191, 0xffff0000, v80
	v_lshlrev_b32_e32 v192, 16, v81
	v_and_b32_e32 v193, 0xffff0000, v81
	v_mul_f32_e32 v190, 0xbfb8aa3b, v190
	v_mul_f32_e32 v191, 0xbfb8aa3b, v191
	v_mul_f32_e32 v192, 0xbfb8aa3b, v192
	v_mul_f32_e32 v193, 0xbfb8aa3b, v193
; __device__ __forceinline__ unsigned pk2(float lo, float hi) { f32x2_t v = {lo, hi}; bf16x2_t b = __builtin_convertvector(v, bf16x2_t); return __builtin_bit_cast(unsigned, b); }
; __device__ __forceinline__ float sigmoidf_(float x) { return __builtin_amdgcn_rcpf(1.0f + __expf(-x)); }
; __global__ void __launch_bounds__(NTHREADS, 2) fwd_megakernel(Params P) {
;     ...
;                 const float rsn = 1.0f / sqrtf(ss * (1.0f / 256.0f) + NORM_EPS);
;                 const f32x4 wn = *(const f32x4*)(q_mnw + l * 1024 + h * 256 + 4 * lane);
;                 u32x2 ow;
;                 ow.x = pk2(x[0] * rsn * wn[0] * sigmoidf_(bflo(mo[q].x)), x[1] * rsn * wn[1] * sigmoidf_(bfhi(mo[q].x)));
;                 ow.y = pk2(x[2] * rsn * wn[2] * sigmoidf_(bflo(mo[q].y)), x[3] * rsn * wn[3] * sigmoidf_(bfhi(mo[q].y)));
;                 if (ok[q]) *(u32x2*)(q_hcat + (size_t)row * 1024 + h * 256 + 4 * lane) = ow;
	v_exp_f32_e32 v190, v190
	v_exp_f32_e32 v191, v191
	v_exp_f32_e32 v192, v192
	v_exp_f32_e32 v193, v193
	v_add_f32_e32 v190, 1.0, v190
	v_add_f32_e32 v191, 1.0, v191
	v_add_f32_e32 v192, 1.0, v192
	v_add_f32_e32 v193, 1.0, v193
	v_rcp_f32_e32 v190, v190
	v_rcp_f32_e32 v191, v191
	v_rcp_f32_e32 v192, v192
	v_rcp_f32_e32 v193, v193
	v_mul_f32_e32 v172, v190, v172
	v_mul_f32_e32 v173, v191, v173
	v_mul_f32_e32 v174, v192, v174
	v_mul_f32_e32 v175, v193, v175
	v_cvt_pk_bf16_f32 v194, v172, v173
	v_cvt_pk_bf16_f32 v195, v174, v175
	global_store_dwordx2 v33, v[194:195], s[38:39]
	v_add_u32_e32 v33, 0x100000, v33
	v_fmamk_f32 v182, v182, 0x3b800000, v214
	v_cmp_gt_f32_e32 vcc, s66, v182
	v_mul_f32_e32 v190, 0x4f800000, v182
	s_nop 0
	v_cndmask_b32_e32 v182, v182, v190, vcc
	v_sqrt_f32_e32 v190, v182
	s_nop 0
	v_add_u32_e32 v191, -1, v190
	v_fma_f32 v192, -v191, v190, v182
	v_cmp_ge_f32_e64 s[40:41], 0, v192
	v_add_u32_e32 v192, 1, v190
	s_nop 0
	v_cndmask_b32_e64 v191, v190, v191, s[40:41]
	v_fma_f32 v190, -v192, v190, v182
	v_cmp_lt_f32_e64 s[40:41], 0, v190
	s_nop 1
	v_cndmask_b32_e64 v190, v191, v192, s[40:41]
	v_mul_f32_e32 v191, 0x37800000, v190
	v_cndmask_b32_e32 v190, v190, v191, vcc
	v_cmp_class_f32_e32 vcc, v182, v215
	s_nop 1
	v_cndmask_b32_e32 v182, v190, v182, vcc
	v_div_scale_f32 v196, s[52:53], v182, v182, 1.0
	v_rcp_f32_e32 v197, v196
	s_nop 0
	v_fma_f32 v198, -v196, v197, 1.0
	v_fmac_f32_e32 v197, v198, v197
	v_div_scale_f32 v198, vcc, 1.0, v182, 1.0
	v_mul_f32_e32 v199, v198, v197
	v_fma_f32 v195, -v196, v199, v198
	v_fmac_f32_e32 v199, v195, v197
	v_fma_f32 v196, -v196, v199, v198
	v_div_fmas_f32 v196, v196, v197, v199
	v_div_fixup_f32 v195, v196, v182, 1.0
	v_mul_f32_e32 v178, v178, v195
	v_mul_f32_e32 v179, v179, v195
	v_mul_f32_e32 v180, v180, v195
	v_mul_f32_e32 v181, v181, v195
	v_mul_f32_e32 v178, v178, v20
	v_mul_f32_e32 v179, v179, v21
	v_mul_f32_e32 v180, v180, v22
	v_mul_f32_e32 v181, v181, v23
	v_lshlrev_b32_e32 v190, 16, v94
	v_and_b32_e32 v191, 0xffff0000, v94
	v_lshlrev_b32_e32 v192, 16, v95
	v_and_b32_e32 v193, 0xffff0000, v95
	v_mul_f32_e32 v190, 0xbfb8aa3b, v190
	v_mul_f32_e32 v191, 0xbfb8aa3b, v191
	v_mul_f32_e32 v192, 0xbfb8aa3b, v192
	v_mul_f32_e32 v193, 0xbfb8aa3b, v193
	v_exp_f32_e32 v190, v190
	v_exp_f32_e32 v191, v191
	v_exp_f32_e32 v192, v192
	v_exp_f32_e32 v193, v193
	v_add_f32_e32 v190, 1.0, v190
	v_add_f32_e32 v191, 1.0, v191
	v_add_f32_e32 v192, 1.0, v192
	v_add_f32_e32 v193, 1.0, v193
	v_rcp_f32_e32 v190, v190
	v_rcp_f32_e32 v191, v191
	v_rcp_f32_e32 v192, v192
	v_rcp_f32_e32 v193, v193
	v_mul_f32_e32 v178, v190, v178
	v_mul_f32_e32 v179, v191, v179
	v_mul_f32_e32 v180, v192, v180
	v_mul_f32_e32 v181, v193, v181
	v_cvt_pk_bf16_f32 v194, v178, v179
	v_cvt_pk_bf16_f32 v195, v180, v181
	global_store_dwordx2 v33, v[194:195], s[38:39]
	v_add_u32_e32 v33, 0x100000, v33
	v_fmamk_f32 v188, v188, 0x3b800000, v214
	v_cmp_gt_f32_e32 vcc, s66, v188
	v_mul_f32_e32 v190, 0x4f800000, v188
	s_nop 0
	v_cndmask_b32_e32 v188, v188, v190, vcc
	v_sqrt_f32_e32 v190, v188
	s_nop 0
	v_add_u32_e32 v191, -1, v190
	v_fma_f32 v192, -v191, v190, v188
	v_cmp_ge_f32_e64 s[40:41], 0, v192
	v_add_u32_e32 v192, 1, v190
	s_nop 0
	v_cndmask_b32_e64 v191, v190, v191, s[40:41]
	v_fma_f32 v190, -v192, v190, v188
	v_cmp_lt_f32_e64 s[40:41], 0, v190
	s_nop 1
	v_cndmask_b32_e64 v190, v191, v192, s[40:41]
	v_mul_f32_e32 v191, 0x37800000, v190
	v_cndmask_b32_e32 v190, v190, v191, vcc
	v_cmp_class_f32_e32 vcc, v188, v215
	s_nop 1
	v_cndmask_b32_e32 v188, v190, v188, vcc
	v_div_scale_f32 v196, s[52:53], v188, v188, 1.0
	v_rcp_f32_e32 v197, v196
	s_nop 0
	v_fma_f32 v198, -v196, v197, 1.0
	v_fmac_f32_e32 v197, v198, v197
	v_div_scale_f32 v198, vcc, 1.0, v188, 1.0
	v_mul_f32_e32 v199, v198, v197
	v_fma_f32 v195, -v196, v199, v198
	v_fmac_f32_e32 v199, v195, v197
	v_fma_f32 v196, -v196, v199, v198
	v_div_fmas_f32 v196, v196, v197, v199
	v_div_fixup_f32 v195, v196, v188, 1.0
	v_mul_f32_e32 v184, v184, v195
	v_mul_f32_e32 v185, v185, v195
	v_mul_f32_e32 v186, v186, v195
	v_mul_f32_e32 v187, v187, v195
	v_mul_f32_e32 v184, v184, v20
	v_mul_f32_e32 v185, v185, v21
	v_mul_f32_e32 v186, v186, v22
	v_mul_f32_e32 v187, v187, v23
	v_lshlrev_b32_e32 v190, 16, v108
	v_and_b32_e32 v191, 0xffff0000, v108
	v_lshlrev_b32_e32 v192, 16, v109
	v_and_b32_e32 v193, 0xffff0000, v109
	v_mul_f32_e32 v190, 0xbfb8aa3b, v190
	v_mul_f32_e32 v191, 0xbfb8aa3b, v191
	v_mul_f32_e32 v192, 0xbfb8aa3b, v192
	v_mul_f32_e32 v193, 0xbfb8aa3b, v193
	v_exp_f32_e32 v190, v190
	v_exp_f32_e32 v191, v191
	v_exp_f32_e32 v192, v192
	v_exp_f32_e32 v193, v193
	v_add_f32_e32 v190, 1.0, v190
	v_add_f32_e32 v191, 1.0, v191
	v_add_f32_e32 v192, 1.0, v192
	v_add_f32_e32 v193, 1.0, v193
	v_rcp_f32_e32 v190, v190
	v_rcp_f32_e32 v191, v191
	v_rcp_f32_e32 v192, v192
	v_rcp_f32_e32 v193, v193
	v_mul_f32_e32 v184, v190, v184
	v_mul_f32_e32 v185, v191, v185
	v_mul_f32_e32 v186, v192, v186
	v_mul_f32_e32 v187, v193, v187
	v_cvt_pk_bf16_f32 v194, v184, v185
	v_cvt_pk_bf16_f32 v195, v186, v187
	global_store_dwordx2 v33, v[194:195], s[38:39]
	v_add_u32_e32 v33, 0x100000, v33
	s_waitcnt vmcnt(0)
; __global__ void __launch_bounds__(NTHREADS, 2) fwd_megakernel(Params P) {
;     ...
;                 v[q] = (f32x4){0.f, 0.f, 0.f, 0.f}; den[q] = 0.f;
; #pragma unroll
;                 for (int dq = 0; dq < 4; ++dq) { const u32x2 p = *(const u32x2*)(q_mp + (size_t)dq * T * 1024 + o);
;                     v[q][0] += bflo(p.x); v[q][1] += bfhi(p.x); v[q][2] += bflo(p.y); v[q][3] += bfhi(p.y); den[q] += q_dp[(size_t)dq * T * 4 + (size_t)row * 4 + h]; }
;                 mo[q] = *(const u32x2*)(q_proj + (size_t)row * NP + C_MO + h * 256 + 4 * lane);
;             }
; #pragma unroll
;             for (int q = 0; q < 2; ++q) {
;                 const int it = it0 + q * step; const int itc = ok[q] ? it : it0; const int row = itc >> 2, h = itc & 3;
;                 const f32x4 x = v[q] * (1.0f / fmaxf(fabsf(den[q]), 1.0f));
;                 const float ss = wave_sum((x[0] * x[0] + x[1] * x[1]) + (x[2] * x[2] + x[3] * x[3]));
	v_lshlrev_b32_e32 v166, 16, v110
	v_and_b32_e32 v167, 0xffff0000, v110
	v_lshlrev_b32_e32 v168, 16, v111
	v_and_b32_e32 v169, 0xffff0000, v111
	v_lshlrev_b32_e32 v190, 16, v112
	v_and_b32_e32 v191, 0xffff0000, v112
	v_lshlrev_b32_e32 v192, 16, v113
	v_and_b32_e32 v193, 0xffff0000, v113
	v_pk_add_f32 v[166:167], v[166:167], v[190:191]
	v_pk_add_f32 v[168:169], v[168:169], v[192:193]
	v_lshlrev_b32_e32 v190, 16, v114
	v_and_b32_e32 v191, 0xffff0000, v114
	v_lshlrev_b32_e32 v192, 16, v115
	v_and_b32_e32 v193, 0xffff0000, v115
	v_pk_add_f32 v[166:167], v[166:167], v[190:191]
	v_pk_add_f32 v[168:169], v[168:169], v[192:193]
	v_lshlrev_b32_e32 v190, 16, v116
	v_and_b32_e32 v191, 0xffff0000, v116
	v_lshlrev_b32_e32 v192, 16, v117
	v_and_b32_e32 v193, 0xffff0000, v117
	v_pk_add_f32 v[166:167], v[166:167], v[190:191]
	v_pk_add_f32 v[168:169], v[168:169], v[192:193]
	v_add_f32_e32 v194, v118, v119
	v_add_f32_e32 v194, v194, v120
	v_add_f32_e32 v194, v194, v121
	v_max_f32_e64 v194, |v194|, 1.0
	v_div_scale_f32 v196, s[52:53], v194, v194, 1.0
	v_rcp_f32_e32 v197, v196
	s_nop 0
	v_fma_f32 v198, -v196, v197, 1.0
	v_fmac_f32_e32 v197, v198, v197
	v_div_scale_f32 v198, vcc, 1.0, v194, 1.0
	v_mul_f32_e32 v199, v198, v197
	v_fma_f32 v195, -v196, v199, v198
	v_fmac_f32_e32 v199, v195, v197
	v_fma_f32 v196, -v196, v199, v198
	v_div_fmas_f32 v196, v196, v197, v199
	v_div_fixup_f32 v195, v196, v194, 1.0
	v_mul_f32_e32 v166, v166, v195
	v_mul_f32_e32 v167, v167, v195
	v_mul_f32_e32 v168, v168, v195
	v_mul_f32_e32 v169, v169, v195
	v_mul_f32_e32 v190, v166, v166
	v_mul_f32_e32 v191, v167, v167
	v_mul_f32_e32 v192, v168, v168
	v_mul_f32_e32 v193, v169, v169
	v_add_f32_e32 v190, v191, v190
	v_add_f32_e32 v192, v192, v193
	v_add_f32_e32 v170, v190, v192
	v_lshlrev_b32_e32 v172, 16, v124
	v_and_b32_e32 v173, 0xffff0000, v124
	v_lshlrev_b32_e32 v174, 16, v125
	v_and_b32_e32 v175, 0xffff0000, v125
	v_lshlrev_b32_e32 v190, 16, v126
	v_and_b32_e32 v191, 0xffff0000, v126
	v_lshlrev_b32_e32 v192, 16, v127
	v_and_b32_e32 v193, 0xffff0000, v127
	v_pk_add_f32 v[172:173], v[172:173], v[190:191]
	v_pk_add_f32 v[174:175], v[174:175], v[192:193]
	v_lshlrev_b32_e32 v190, 16, v128
	v_and_b32_e32 v191, 0xffff0000, v128
	v_lshlrev_b32_e32 v192, 16, v129
	v_and_b32_e32 v193, 0xffff0000, v129
	v_pk_add_f32 v[172:173], v[172:173], v[190:191]
	v_pk_add_f32 v[174:175], v[174:175], v[192:193]
	v_lshlrev_b32_e32 v190, 16, v130
	v_and_b32_e32 v191, 0xffff0000, v130
	v_lshlrev_b32_e32 v192, 16, v131
	v_and_b32_e32 v193, 0xffff0000, v131
	v_pk_add_f32 v[172:173], v[172:173], v[190:191]
	v_pk_add_f32 v[174:175], v[174:175], v[192:193]
	v_add_f32_e32 v194, v132, v133
	v_add_f32_e32 v194, v194, v134
	v_add_f32_e32 v194, v194, v135
	v_max_f32_e64 v194, |v194|, 1.0
	v_div_scale_f32 v196, s[52:53], v194, v194, 1.0
	v_rcp_f32_e32 v197, v196
	s_nop 0
	v_fma_f32 v198, -v196, v197, 1.0
	v_fmac_f32_e32 v197, v198, v197
	v_div_scale_f32 v198, vcc, 1.0, v194, 1.0
	v_mul_f32_e32 v199, v198, v197
	v_fma_f32 v195, -v196, v199, v198
	v_fmac_f32_e32 v199, v195, v197
	v_fma_f32 v196, -v196, v199, v198
	v_div_fmas_f32 v196, v196, v197, v199
	v_div_fixup_f32 v195, v196, v194, 1.0
	v_mul_f32_e32 v172, v172, v195
	v_mul_f32_e32 v173, v173, v195
	v_mul_f32_e32 v174, v174, v195
	v_mul_f32_e32 v175, v175, v195
	v_mul_f32_e32 v191, v175, v175
	v_mul_f32_e32 v190, v173, v173
	v_fmac_f32_e32 v190, v172, v172
	v_fmac_f32_e32 v191, v174, v174
	v_add_f32_e32 v176, v190, v191
	v_lshlrev_b32_e32 v178, 16, v138
	v_and_b32_e32 v179, 0xffff0000, v138
	v_lshlrev_b32_e32 v180, 16, v139
	v_and_b32_e32 v181, 0xffff0000, v139
	v_lshlrev_b32_e32 v190, 16, v140
	v_and_b32_e32 v191, 0xffff0000, v140
	v_lshlrev_b32_e32 v192, 16, v141
	v_and_b32_e32 v193, 0xffff0000, v141
	v_pk_add_f32 v[178:179], v[178:179], v[190:191]
	v_pk_add_f32 v[180:181], v[180:181], v[192:193]
	v_lshlrev_b32_e32 v190, 16, v142
	v_and_b32_e32 v191, 0xffff0000, v142
	v_lshlrev_b32_e32 v192, 16, v143
	v_and_b32_e32 v193, 0xffff0000, v143
	v_pk_add_f32 v[178:179], v[178:179], v[190:191]
	v_pk_add_f32 v[180:181], v[180:181], v[192:193]
	v_lshlrev_b32_e32 v190, 16, v144
	v_and_b32_e32 v191, 0xffff0000, v144
	v_lshlrev_b32_e32 v192, 16, v145
	v_and_b32_e32 v193, 0xffff0000, v145
	v_pk_add_f32 v[178:179], v[178:179], v[190:191]
	v_pk_add_f32 v[180:181], v[180:181], v[192:193]
	v_add_f32_e32 v194, v146, v147
	v_add_f32_e32 v194, v194, v148
	v_add_f32_e32 v194, v194, v149
	v_max_f32_e64 v194, |v194|, 1.0
	v_div_scale_f32 v196, s[52:53], v194, v194, 1.0
	v_rcp_f32_e32 v197, v196
	s_nop 0
	v_fma_f32 v198, -v196, v197, 1.0
	v_fmac_f32_e32 v197, v198, v197
	v_div_scale_f32 v198, vcc, 1.0, v194, 1.0
	v_mul_f32_e32 v199, v198, v197
	v_fma_f32 v195, -v196, v199, v198
	v_fmac_f32_e32 v199, v195, v197
	v_fma_f32 v196, -v196, v199, v198
	v_div_fmas_f32 v196, v196, v197, v199
	v_div_fixup_f32 v195, v196, v194, 1.0
	v_mul_f32_e32 v178, v178, v195
	v_mul_f32_e32 v179, v179, v195
	v_mul_f32_e32 v180, v180, v195
	v_mul_f32_e32 v181, v181, v195
	v_mul_f32_e32 v190, v178, v178
	v_mul_f32_e32 v191, v179, v179
	v_mul_f32_e32 v192, v180, v180
	v_mul_f32_e32 v193, v181, v181
	v_add_f32_e32 v190, v191, v190
	v_add_f32_e32 v192, v192, v193
	v_add_f32_e32 v182, v190, v192
	v_lshlrev_b32_e32 v184, 16, v152
	v_and_b32_e32 v185, 0xffff0000, v152
	v_lshlrev_b32_e32 v186, 16, v153
	v_and_b32_e32 v187, 0xffff0000, v153
	v_lshlrev_b32_e32 v190, 16, v154
	v_and_b32_e32 v191, 0xffff0000, v154
	v_lshlrev_b32_e32 v192, 16, v155
	v_and_b32_e32 v193, 0xffff0000, v155
	v_pk_add_f32 v[184:185], v[184:185], v[190:191]
	v_pk_add_f32 v[186:187], v[186:187], v[192:193]
	v_lshlrev_b32_e32 v190, 16, v156
; __device__ __forceinline__ unsigned pk2(float lo, float hi) { f32x2_t v = {lo, hi}; bf16x2_t b = __builtin_convertvector(v, bf16x2_t); return __builtin_bit_cast(unsigned, b); }
; __device__ __forceinline__ float sigmoidf_(float x) { return __builtin_amdgcn_rcpf(1.0f + __expf(-x)); }
; __global__ void __launch_bounds__(NTHREADS, 2) fwd_megakernel(Params P) {
;     ...
;                 for (int dq = 0; dq < 4; ++dq) { const u32x2 p = *(const u32x2*)(q_mp + (size_t)dq * T * 1024 + o);
;                     v[q][0] += bflo(p.x); v[q][1] += bfhi(p.x); v[q][2] += bflo(p.y); v[q][3] += bfhi(p.y); den[q] += q_dp[(size_t)dq * T * 4 + (size_t)row * 4 + h]; }
;                 mo[q] = *(const u32x2*)(q_proj + (size_t)row * NP + C_MO + h * 256 + 4 * lane);
;             }
; #pragma unroll
;             for (int q = 0; q < 2; ++q) {
;                 const int it = it0 + q * step; const int itc = ok[q] ? it : it0; const int row = itc >> 2, h = itc & 3;
;                 const f32x4 x = v[q] * (1.0f / fmaxf(fabsf(den[q]), 1.0f));
;                 const float ss = wave_sum((x[0] * x[0] + x[1] * x[1]) + (x[2] * x[2] + x[3] * x[3]));
;                 const float rsn = 1.0f / sqrtf(ss * (1.0f / 256.0f) + NORM_EPS);
;                 const f32x4 wn = *(const f32x4*)(q_mnw + l * 1024 + h * 256 + 4 * lane);
;                 u32x2 ow;
;                 ow.x = pk2(x[0] * rsn * wn[0] * sigmoidf_(bflo(mo[q].x)), x[1] * rsn * wn[1] * sigmoidf_(bfhi(mo[q].x)));
;                 ow.y = pk2(x[2] * rsn * wn[2] * sigmoidf_(bflo(mo[q].y)), x[3] * rsn * wn[3] * sigmoidf_(bfhi(mo[q].y)));
;                 if (ok[q]) *(u32x2*)(q_hcat + (size_t)row * 1024 + h * 256 + 4 * lane) = ow;
	v_and_b32_e32 v191, 0xffff0000, v156
	v_lshlrev_b32_e32 v192, 16, v157
	v_and_b32_e32 v193, 0xffff0000, v157
	v_pk_add_f32 v[184:185], v[184:185], v[190:191]
	v_pk_add_f32 v[186:187], v[186:187], v[192:193]
	v_lshlrev_b32_e32 v190, 16, v158
	v_and_b32_e32 v191, 0xffff0000, v158
	v_lshlrev_b32_e32 v192, 16, v159
	v_and_b32_e32 v193, 0xffff0000, v159
	v_pk_add_f32 v[184:185], v[184:185], v[190:191]
	v_pk_add_f32 v[186:187], v[186:187], v[192:193]
	v_add_f32_e32 v194, v160, v161
	v_add_f32_e32 v194, v194, v162
	v_add_f32_e32 v194, v194, v163
	v_max_f32_e64 v194, |v194|, 1.0
	v_div_scale_f32 v196, s[52:53], v194, v194, 1.0
	v_rcp_f32_e32 v197, v196
	s_nop 0
	v_fma_f32 v198, -v196, v197, 1.0
	v_fmac_f32_e32 v197, v198, v197
	v_div_scale_f32 v198, vcc, 1.0, v194, 1.0
	v_mul_f32_e32 v199, v198, v197
	v_fma_f32 v195, -v196, v199, v198
	v_fmac_f32_e32 v199, v195, v197
	v_fma_f32 v196, -v196, v199, v198
	v_div_fmas_f32 v196, v196, v197, v199
	v_div_fixup_f32 v195, v196, v194, 1.0
	v_mul_f32_e32 v184, v184, v195
	v_mul_f32_e32 v185, v185, v195
	v_mul_f32_e32 v186, v186, v195
	v_mul_f32_e32 v187, v187, v195
	v_mul_f32_e32 v191, v187, v187
	v_mul_f32_e32 v190, v185, v185
	v_fmac_f32_e32 v190, v184, v184
	v_fmac_f32_e32 v191, v186, v186
	v_add_f32_e32 v188, v190, v191
	s_nop 1
	v_mov_b32_dpp v171, v170 quad_perm:[1,0,3,2] row_mask:0xf bank_mask:0xf
	v_mov_b32_dpp v177, v176 quad_perm:[1,0,3,2] row_mask:0xf bank_mask:0xf
	v_mov_b32_dpp v183, v182 quad_perm:[1,0,3,2] row_mask:0xf bank_mask:0xf
	v_mov_b32_dpp v189, v188 quad_perm:[1,0,3,2] row_mask:0xf bank_mask:0xf
	v_add_f32_e32 v170, v170, v171
	v_add_f32_e32 v176, v176, v177
	v_add_f32_e32 v182, v182, v183
	v_add_f32_e32 v188, v188, v189
	s_nop 1
	v_mov_b32_dpp v171, v170 quad_perm:[2,3,0,1] row_mask:0xf bank_mask:0xf
	v_mov_b32_dpp v177, v176 quad_perm:[2,3,0,1] row_mask:0xf bank_mask:0xf
	v_mov_b32_dpp v183, v182 quad_perm:[2,3,0,1] row_mask:0xf bank_mask:0xf
	v_mov_b32_dpp v189, v188 quad_perm:[2,3,0,1] row_mask:0xf bank_mask:0xf
	v_add_f32_e32 v170, v170, v171
	v_add_f32_e32 v176, v176, v177
	v_add_f32_e32 v182, v182, v183
	v_add_f32_e32 v188, v188, v189
	s_nop 1
	v_mov_b32_dpp v171, v170 row_half_mirror row_mask:0xf bank_mask:0xf
	v_mov_b32_dpp v177, v176 row_half_mirror row_mask:0xf bank_mask:0xf
	v_mov_b32_dpp v183, v182 row_half_mirror row_mask:0xf bank_mask:0xf
	v_mov_b32_dpp v189, v188 row_half_mirror row_mask:0xf bank_mask:0xf
	v_add_f32_e32 v170, v170, v171
	v_add_f32_e32 v176, v176, v177
	v_add_f32_e32 v182, v182, v183
	v_add_f32_e32 v188, v188, v189
	s_nop 1
	v_mov_b32_dpp v171, v170 row_mirror row_mask:0xf bank_mask:0xf
	v_mov_b32_dpp v177, v176 row_mirror row_mask:0xf bank_mask:0xf
	v_mov_b32_dpp v183, v182 row_mirror row_mask:0xf bank_mask:0xf
	v_mov_b32_dpp v189, v188 row_mirror row_mask:0xf bank_mask:0xf
	v_add_f32_e32 v170, v170, v171
	v_add_f32_e32 v176, v176, v177
	v_add_f32_e32 v182, v182, v183
	v_add_f32_e32 v188, v188, v189
	v_mov_b32_e32 v171, v170
	v_mov_b32_e32 v177, v176
	v_mov_b32_e32 v183, v182
	v_mov_b32_e32 v189, v188
	s_nop 1
	v_permlane16_swap_b32 v171, v170
	v_permlane16_swap_b32 v177, v176
	v_permlane16_swap_b32 v183, v182
	v_permlane16_swap_b32 v189, v188
	v_add_f32_e32 v170, v170, v171
	v_add_f32_e32 v176, v176, v177
	v_add_f32_e32 v182, v182, v183
	v_add_f32_e32 v188, v188, v189
	v_mov_b32_e32 v171, v170
	v_mov_b32_e32 v177, v176
	v_mov_b32_e32 v183, v182
	v_mov_b32_e32 v189, v188
	s_nop 1
	v_permlane32_swap_b32 v171, v170
	v_permlane32_swap_b32 v177, v176
	v_permlane32_swap_b32 v183, v182
	v_permlane32_swap_b32 v189, v188
	v_add_f32_e32 v170, v170, v171
	v_add_f32_e32 v176, v176, v177
	v_add_f32_e32 v182, v182, v183
	v_add_f32_e32 v188, v188, v189
	v_fmamk_f32 v170, v170, 0x3b800000, v214
	v_cmp_gt_f32_e32 vcc, s66, v170
	v_mul_f32_e32 v190, 0x4f800000, v170
	s_nop 0
	v_cndmask_b32_e32 v170, v170, v190, vcc
	v_sqrt_f32_e32 v190, v170
	s_nop 0
	v_add_u32_e32 v191, -1, v190
	v_fma_f32 v192, -v191, v190, v170
	v_cmp_ge_f32_e64 s[40:41], 0, v192
	v_add_u32_e32 v192, 1, v190
	s_nop 0
	v_cndmask_b32_e64 v191, v190, v191, s[40:41]
	v_fma_f32 v190, -v192, v190, v170
	v_cmp_lt_f32_e64 s[40:41], 0, v190
	s_nop 1
	v_cndmask_b32_e64 v190, v191, v192, s[40:41]
	v_mul_f32_e32 v191, 0x37800000, v190
	v_cndmask_b32_e32 v190, v190, v191, vcc
	v_cmp_class_f32_e32 vcc, v170, v215
	s_nop 1
	v_cndmask_b32_e32 v170, v190, v170, vcc
	v_div_scale_f32 v196, s[52:53], v170, v170, 1.0
	v_rcp_f32_e32 v197, v196
	s_nop 0
	v_fma_f32 v198, -v196, v197, 1.0
	v_fmac_f32_e32 v197, v198, v197
	v_div_scale_f32 v198, vcc, 1.0, v170, 1.0
	v_mul_f32_e32 v199, v198, v197
	v_fma_f32 v195, -v196, v199, v198
	v_fmac_f32_e32 v199, v195, v197
	v_fma_f32 v196, -v196, v199, v198
	v_div_fmas_f32 v196, v196, v197, v199
	v_div_fixup_f32 v195, v196, v170, 1.0
	v_mul_f32_e32 v166, v166, v195
	v_mul_f32_e32 v167, v167, v195
	v_mul_f32_e32 v168, v168, v195
	v_mul_f32_e32 v169, v169, v195
	v_mul_f32_e32 v166, v166, v20
	v_mul_f32_e32 v167, v167, v21
	v_mul_f32_e32 v168, v168, v22
	v_mul_f32_e32 v169, v169, v23
	v_lshlrev_b32_e32 v190, 16, v122
	v_and_b32_e32 v191, 0xffff0000, v122
	v_lshlrev_b32_e32 v192, 16, v123
	v_and_b32_e32 v193, 0xffff0000, v123
	v_mul_f32_e32 v190, 0xbfb8aa3b, v190
	v_mul_f32_e32 v191, 0xbfb8aa3b, v191
	v_mul_f32_e32 v192, 0xbfb8aa3b, v192
	v_mul_f32_e32 v193, 0xbfb8aa3b, v193
	v_exp_f32_e32 v190, v190
	v_exp_f32_e32 v191, v191
	v_exp_f32_e32 v192, v192
	v_exp_f32_e32 v193, v193
	v_add_f32_e32 v190, 1.0, v190
	v_add_f32_e32 v191, 1.0, v191
	v_add_f32_e32 v192, 1.0, v192
	v_add_f32_e32 v193, 1.0, v193
	v_rcp_f32_e32 v190, v190
	v_rcp_f32_e32 v191, v191
	v_rcp_f32_e32 v192, v192
; __device__ __forceinline__ unsigned pk2(float lo, float hi) { f32x2_t v = {lo, hi}; bf16x2_t b = __builtin_convertvector(v, bf16x2_t); return __builtin_bit_cast(unsigned, b); }
; __device__ __forceinline__ float sigmoidf_(float x) { return __builtin_amdgcn_rcpf(1.0f + __expf(-x)); }
; __global__ void __launch_bounds__(NTHREADS, 2) fwd_megakernel(Params P) {
;     ...
;                 const float rsn = 1.0f / sqrtf(ss * (1.0f / 256.0f) + NORM_EPS);
;                 const f32x4 wn = *(const f32x4*)(q_mnw + l * 1024 + h * 256 + 4 * lane);
;                 u32x2 ow;
;                 ow.x = pk2(x[0] * rsn * wn[0] * sigmoidf_(bflo(mo[q].x)), x[1] * rsn * wn[1] * sigmoidf_(bfhi(mo[q].x)));
;                 ow.y = pk2(x[2] * rsn * wn[2] * sigmoidf_(bflo(mo[q].y)), x[3] * rsn * wn[3] * sigmoidf_(bfhi(mo[q].y)));
;                 if (ok[q]) *(u32x2*)(q_hcat + (size_t)row * 1024 + h * 256 + 4 * lane) = ow;
	v_rcp_f32_e32 v193, v193
	v_mul_f32_e32 v166, v190, v166
	v_mul_f32_e32 v167, v191, v167
	v_mul_f32_e32 v168, v192, v168
	v_mul_f32_e32 v169, v193, v169
	v_cvt_pk_bf16_f32 v194, v166, v167
	v_cvt_pk_bf16_f32 v195, v168, v169
	global_store_dwordx2 v33, v[194:195], s[38:39]
	v_add_u32_e32 v33, 0x100000, v33
	v_fmamk_f32 v176, v176, 0x3b800000, v214
	v_cmp_gt_f32_e32 vcc, s66, v176
	v_mul_f32_e32 v190, 0x4f800000, v176
	s_nop 0
	v_cndmask_b32_e32 v176, v176, v190, vcc
	v_sqrt_f32_e32 v190, v176
	s_nop 0
	v_add_u32_e32 v191, -1, v190
	v_fma_f32 v192, -v191, v190, v176
	v_cmp_ge_f32_e64 s[40:41], 0, v192
	v_add_u32_e32 v192, 1, v190
	s_nop 0
	v_cndmask_b32_e64 v191, v190, v191, s[40:41]
	v_fma_f32 v190, -v192, v190, v176
	v_cmp_lt_f32_e64 s[40:41], 0, v190
	s_nop 1
	v_cndmask_b32_e64 v190, v191, v192, s[40:41]
	v_mul_f32_e32 v191, 0x37800000, v190
	v_cndmask_b32_e32 v190, v190, v191, vcc
	v_cmp_class_f32_e32 vcc, v176, v215
	s_nop 1
	v_cndmask_b32_e32 v176, v190, v176, vcc
	v_div_scale_f32 v196, s[52:53], v176, v176, 1.0
	v_rcp_f32_e32 v197, v196
	s_nop 0
	v_fma_f32 v198, -v196, v197, 1.0
	v_fmac_f32_e32 v197, v198, v197
	v_div_scale_f32 v198, vcc, 1.0, v176, 1.0
	v_mul_f32_e32 v199, v198, v197
	v_fma_f32 v195, -v196, v199, v198
	v_fmac_f32_e32 v199, v195, v197
	v_fma_f32 v196, -v196, v199, v198
	v_div_fmas_f32 v196, v196, v197, v199
	v_div_fixup_f32 v195, v196, v176, 1.0
	v_mul_f32_e32 v172, v172, v195
	v_mul_f32_e32 v173, v173, v195
	v_mul_f32_e32 v174, v174, v195
	v_mul_f32_e32 v175, v175, v195
	v_mul_f32_e32 v172, v172, v20
	v_mul_f32_e32 v173, v173, v21
	v_mul_f32_e32 v174, v174, v22
	v_mul_f32_e32 v175, v175, v23
	v_lshlrev_b32_e32 v190, 16, v136
	v_and_b32_e32 v191, 0xffff0000, v136
	v_lshlrev_b32_e32 v192, 16, v137
	v_and_b32_e32 v193, 0xffff0000, v137
	v_mul_f32_e32 v190, 0xbfb8aa3b, v190
	v_mul_f32_e32 v191, 0xbfb8aa3b, v191
	v_mul_f32_e32 v192, 0xbfb8aa3b, v192
	v_mul_f32_e32 v193, 0xbfb8aa3b, v193
	v_exp_f32_e32 v190, v190
	v_exp_f32_e32 v191, v191
	v_exp_f32_e32 v192, v192
	v_exp_f32_e32 v193, v193
	v_add_f32_e32 v190, 1.0, v190
	v_add_f32_e32 v191, 1.0, v191
	v_add_f32_e32 v192, 1.0, v192
	v_add_f32_e32 v193, 1.0, v193
	v_rcp_f32_e32 v190, v190
	v_rcp_f32_e32 v191, v191
	v_rcp_f32_e32 v192, v192
	v_rcp_f32_e32 v193, v193
	v_mul_f32_e32 v172, v190, v172
	v_mul_f32_e32 v173, v191, v173
	v_mul_f32_e32 v174, v192, v174
	v_mul_f32_e32 v175, v193, v175
	v_cvt_pk_bf16_f32 v194, v172, v173
	v_cvt_pk_bf16_f32 v195, v174, v175
	global_store_dwordx2 v33, v[194:195], s[38:39]
	v_add_u32_e32 v33, 0x100000, v33
	v_fmamk_f32 v182, v182, 0x3b800000, v214
	v_cmp_gt_f32_e32 vcc, s66, v182
	v_mul_f32_e32 v190, 0x4f800000, v182
	s_nop 0
	v_cndmask_b32_e32 v182, v182, v190, vcc
	v_sqrt_f32_e32 v190, v182
	s_nop 0
	v_add_u32_e32 v191, -1, v190
	v_fma_f32 v192, -v191, v190, v182
	v_cmp_ge_f32_e64 s[40:41], 0, v192
	v_add_u32_e32 v192, 1, v190
	s_nop 0
	v_cndmask_b32_e64 v191, v190, v191, s[40:41]
	v_fma_f32 v190, -v192, v190, v182
	v_cmp_lt_f32_e64 s[40:41], 0, v190
	s_nop 1
	v_cndmask_b32_e64 v190, v191, v192, s[40:41]
	v_mul_f32_e32 v191, 0x37800000, v190
	v_cndmask_b32_e32 v190, v190, v191, vcc
	v_cmp_class_f32_e32 vcc, v182, v215
	s_nop 1
	v_cndmask_b32_e32 v182, v190, v182, vcc
	v_div_scale_f32 v196, s[52:53], v182, v182, 1.0
	v_rcp_f32_e32 v197, v196
	s_nop 0
	v_fma_f32 v198, -v196, v197, 1.0
	v_fmac_f32_e32 v197, v198, v197
	v_div_scale_f32 v198, vcc, 1.0, v182, 1.0
	v_mul_f32_e32 v199, v198, v197
	v_fma_f32 v195, -v196, v199, v198
	v_fmac_f32_e32 v199, v195, v197
	v_fma_f32 v196, -v196, v199, v198
; __device__ __forceinline__ unsigned pk2(float lo, float hi) { f32x2_t v = {lo, hi}; bf16x2_t b = __builtin_convertvector(v, bf16x2_t); return __builtin_bit_cast(unsigned, b); }
; __device__ __forceinline__ float sigmoidf_(float x) { return __builtin_amdgcn_rcpf(1.0f + __expf(-x)); }
; __global__ void __launch_bounds__(NTHREADS, 2) fwd_megakernel(Params P) {
;     ...
;                 const float rsn = 1.0f / sqrtf(ss * (1.0f / 256.0f) + NORM_EPS);
;                 const f32x4 wn = *(const f32x4*)(q_mnw + l * 1024 + h * 256 + 4 * lane);
;                 u32x2 ow;
;                 ow.x = pk2(x[0] * rsn * wn[0] * sigmoidf_(bflo(mo[q].x)), x[1] * rsn * wn[1] * sigmoidf_(bfhi(mo[q].x)));
;                 ow.y = pk2(x[2] * rsn * wn[2] * sigmoidf_(bflo(mo[q].y)), x[3] * rsn * wn[3] * sigmoidf_(bfhi(mo[q].y)));
;                 if (ok[q]) *(u32x2*)(q_hcat + (size_t)row * 1024 + h * 256 + 4 * lane) = ow;
	v_div_fmas_f32 v196, v196, v197, v199
	v_div_fixup_f32 v195, v196, v182, 1.0
	v_mul_f32_e32 v178, v178, v195
	v_mul_f32_e32 v179, v179, v195
	v_mul_f32_e32 v180, v180, v195
	v_mul_f32_e32 v181, v181, v195
	v_mul_f32_e32 v178, v178, v20
	v_mul_f32_e32 v179, v179, v21
	v_mul_f32_e32 v180, v180, v22
	v_mul_f32_e32 v181, v181, v23
	v_lshlrev_b32_e32 v190, 16, v150
	v_and_b32_e32 v191, 0xffff0000, v150
	v_lshlrev_b32_e32 v192, 16, v151
	v_and_b32_e32 v193, 0xffff0000, v151
	v_mul_f32_e32 v190, 0xbfb8aa3b, v190
	v_mul_f32_e32 v191, 0xbfb8aa3b, v191
	v_mul_f32_e32 v192, 0xbfb8aa3b, v192
	v_mul_f32_e32 v193, 0xbfb8aa3b, v193
	v_exp_f32_e32 v190, v190
	v_exp_f32_e32 v191, v191
	v_exp_f32_e32 v192, v192
	v_exp_f32_e32 v193, v193
	v_add_f32_e32 v190, 1.0, v190
	v_add_f32_e32 v191, 1.0, v191
	v_add_f32_e32 v192, 1.0, v192
	v_add_f32_e32 v193, 1.0, v193
	v_rcp_f32_e32 v190, v190
	v_rcp_f32_e32 v191, v191
	v_rcp_f32_e32 v192, v192
	v_rcp_f32_e32 v193, v193
	v_mul_f32_e32 v178, v190, v178
	v_mul_f32_e32 v179, v191, v179
	v_mul_f32_e32 v180, v192, v180
	v_mul_f32_e32 v181, v193, v181
	v_cvt_pk_bf16_f32 v194, v178, v179
	v_cvt_pk_bf16_f32 v195, v180, v181
	global_store_dwordx2 v33, v[194:195], s[38:39]
	v_add_u32_e32 v33, 0x100000, v33
	v_fmamk_f32 v188, v188, 0x3b800000, v214
	v_cmp_gt_f32_e32 vcc, s66, v188
	v_mul_f32_e32 v190, 0x4f800000, v188
	s_nop 0
	v_cndmask_b32_e32 v188, v188, v190, vcc
	v_sqrt_f32_e32 v190, v188
	s_nop 0
	v_add_u32_e32 v191, -1, v190
	v_fma_f32 v192, -v191, v190, v188
	v_cmp_ge_f32_e64 s[40:41], 0, v192
	v_add_u32_e32 v192, 1, v190
	s_nop 0
	v_cndmask_b32_e64 v191, v190, v191, s[40:41]
	v_fma_f32 v190, -v192, v190, v188
	v_cmp_lt_f32_e64 s[40:41], 0, v190
	s_nop 1
	v_cndmask_b32_e64 v190, v191, v192, s[40:41]
	v_mul_f32_e32 v191, 0x37800000, v190
	v_cndmask_b32_e32 v190, v190, v191, vcc
	v_cmp_class_f32_e32 vcc, v188, v215
	s_nop 1
	v_cndmask_b32_e32 v188, v190, v188, vcc
	v_div_scale_f32 v196, s[52:53], v188, v188, 1.0
	v_rcp_f32_e32 v197, v196
	s_nop 0
	v_fma_f32 v198, -v196, v197, 1.0
	v_fmac_f32_e32 v197, v198, v197
	v_div_scale_f32 v198, vcc, 1.0, v188, 1.0
	v_mul_f32_e32 v199, v198, v197
	v_fma_f32 v195, -v196, v199, v198
	v_fmac_f32_e32 v199, v195, v197
	v_fma_f32 v196, -v196, v199, v198
	v_div_fmas_f32 v196, v196, v197, v199
	v_div_fixup_f32 v195, v196, v188, 1.0
	v_mul_f32_e32 v184, v184, v195
	v_mul_f32_e32 v185, v185, v195
	v_mul_f32_e32 v186, v186, v195
	v_mul_f32_e32 v187, v187, v195
	v_mul_f32_e32 v184, v184, v20
	v_mul_f32_e32 v185, v185, v21
	v_mul_f32_e32 v186, v186, v22
	v_mul_f32_e32 v187, v187, v23
	v_lshlrev_b32_e32 v190, 16, v164
	v_and_b32_e32 v191, 0xffff0000, v164
	v_lshlrev_b32_e32 v192, 16, v165
	v_and_b32_e32 v193, 0xffff0000, v165
	v_mul_f32_e32 v190, 0xbfb8aa3b, v190
	v_mul_f32_e32 v191, 0xbfb8aa3b, v191
	v_mul_f32_e32 v192, 0xbfb8aa3b, v192
	v_mul_f32_e32 v193, 0xbfb8aa3b, v193
	v_exp_f32_e32 v190, v190
	v_exp_f32_e32 v191, v191
	v_exp_f32_e32 v192, v192
	v_exp_f32_e32 v193, v193
	v_add_f32_e32 v190, 1.0, v190
	v_add_f32_e32 v191, 1.0, v191
	v_add_f32_e32 v192, 1.0, v192
	v_add_f32_e32 v193, 1.0, v193
	v_rcp_f32_e32 v190, v190
	v_rcp_f32_e32 v191, v191
	v_rcp_f32_e32 v192, v192
	v_rcp_f32_e32 v193, v193
	v_mul_f32_e32 v184, v190, v184
	v_mul_f32_e32 v185, v191, v185
	v_mul_f32_e32 v186, v192, v186
	v_mul_f32_e32 v187, v193, v187
	v_cvt_pk_bf16_f32 v194, v184, v185
	v_cvt_pk_bf16_f32 v195, v186, v187
	global_store_dwordx2 v33, v[194:195], s[38:39]
	v_add_u32_e32 v33, 0x100000, v33
	s_mov_b64 s[52:53], 0
	s_branch .LBB0_546
